# K-loop: 28 s_nop slots between LDS-DMA pairs filled with the segment's last ds_read; M0 writes placed above a ds_read; previous edits
# baseline (speedup 1.0000x reference)
; #define PG8_STAGE(bufoff, gbase, voff) do { _Pragma("unroll") for (int _i = 0; _i < 2; ++_i) \
;         __builtin_amdgcn_global_load_lds((const unsigned*)((const char*)(gbase) + (voff)[_i]), (LAS unsigned*)(lds + (bufoff) + ldsw + _i * 8192), 16, 0, 0); } while (0)
; #define PG8_LDA(dst, b, h) do { _Pragma("unroll") for (int m = 0; m < 4; ++m) _Pragma("unroll") for (int k = 0; k < 2; ++k) dst[m][k] = *(const LAS f16x8*)(lds + PG8_SA(b, h) + aoff + m * 2048 + k * 1024); } while (0)
; #define PG8_LDB(dst, b, h) do { _Pragma("unroll") for (int n = 0; n < 2; ++n) _Pragma("unroll") for (int k = 0; k < 2; ++k) dst[n][k] = *(const LAS f16x8*)(lds + PG8_SB(b, h) + boff + n * 2048 + k * 1024); } while (0)
; #define PG8_MMA(ai, bj, At, Bt) do { __builtin_amdgcn_s_setprio(1); _Pragma("unroll") for (int m = 0; m < 4; ++m) _Pragma("unroll") for (int n = 0; n < 2; ++n) _Pragma("unroll") for (int k = 0; k < 2; ++k) \
;         acc[ai][bj][m][n] = __builtin_amdgcn_mfma_f32_16x16x32_f16(Bt[n][k], At[m][k], acc[ai][bj][m][n], 0, 0, 0); __builtin_amdgcn_s_setprio(0); } while (0)
; #define PG8_WAIT_V(n) asm volatile("s_waitcnt vmcnt(" #n ")" ::: "memory")
; #define PG8_WAIT_L(n) asm volatile("s_waitcnt lgkmcnt(" #n ")" ::: "memory")
; #define PG8_BAR __builtin_amdgcn_s_barrier()
; #define PG8_SCHED __builtin_amdgcn_sched_barrier(0)
; template <class Epi>
; __device__ __forceinline__ void gemm_phase(LAS unsigned char* lds, const Gemm g0, const StaticOrder& S, const Epi& E) {
;     ...
;             const char* a2 = last ? nA : cA + (size_t)(t + 2) * kstep; const char* b2 = last ? nB : cB + (size_t)(t + 2) * kstep;
;             const char* a3 = a2 + kstep; const char* b3 = b2 + kstep;
;             PG8_LDB(B0, 0, 0); PG8_SCHED; PG8_LDA(At, 0, 0); PG8_STAGE(PG8_SA(1, 1), a1 + hstep, voffA);
;             PG8_WAIT_L(8); PG8_BAR; PG8_WAIT_L(0); PG8_MMA(0, 0, At, B0); PG8_BAR; PG8_SCHED;
;             PG8_LDB(B1, 0, 1); PG8_STAGE(PG8_SB(0, 0), b2, voffB);
;             PG8_BAR; PG8_WAIT_L(0); PG8_MMA(0, 1, At, B1); PG8_BAR;
;             PG8_LDA(At, 0, 1); PG8_STAGE(PG8_SA(0, 0), a2, voffA);
;             PG8_BAR; PG8_WAIT_L(0); PG8_MMA(1, 0, At, B0); PG8_BAR; PG8_SCHED;
;             PG8_STAGE(PG8_SB(0, 1), b2 + hstep, voffB);
;             PG8_WAIT_V(6); PG8_BAR; PG8_MMA(1, 1, At, B1); PG8_BAR;
.LBB0_198:
	s_add_u32 s52, s0, 0xfff80080
	s_addc_u32 s53, s1, -1
	s_and_b64 s[22:23], s[50:51], exec
	s_cselect_b32 s53, s75, s53
	s_cselect_b32 s52, s80, s52
	s_add_i32 s84, 0, 0x10000
	ds_read_b128 v[136:139], v161
	ds_read_b128 v[140:143], v161 offset:1024
	ds_read_b128 v[144:147], v161 offset:2048
	ds_read_b128 v[148:151], v161 offset:3072
	s_and_b64 s[22:23], s[50:51], exec
	s_cselect_b32 s51, s81, s25
	s_cselect_b32 s50, s82, s24
	s_add_i32 m0, s28, 0xc000
	ds_read_b128 v[152:155], v222
	ds_read_b128 v[156:159], v222 offset:1024
	ds_read_b128 v[186:189], v222 offset:2048
	ds_read_b128 v[190:193], v222 offset:3072
	ds_read_b128 v[194:197], v222 offset:4096
	ds_read_b128 v[198:201], v222 offset:5120
	ds_read_b128 v[202:205], v222 offset:6144
	global_load_lds_dwordx4 v184, s[0:1]
	s_add_i32 m0, s28, 0xe000
	ds_read_b128 v[206:209], v222 offset:7168
	global_load_lds_dwordx4 v182, s[0:1]
	s_waitcnt lgkmcnt(8)
	s_barrier
	s_waitcnt lgkmcnt(0)
	s_waitcnt lgkmcnt(0)
	v_mfma_f32_16x16x32_f16 v[126:129], v[136:139], v[152:155], v[126:129]
	v_mfma_f32_16x16x32_f16 v[122:125], v[144:147], v[152:155], v[122:125]
	v_mfma_f32_16x16x32_f16 v[118:121], v[136:139], v[186:189], v[118:121]
	v_mfma_f32_16x16x32_f16 v[110:113], v[144:147], v[186:189], v[110:113]
	v_mfma_f32_16x16x32_f16 v[102:105], v[136:139], v[194:197], v[102:105]
	v_mfma_f32_16x16x32_f16 v[98:101], v[144:147], v[194:197], v[98:101]
	v_mfma_f32_16x16x32_f16 v[86:89], v[136:139], v[202:205], v[86:89]
	v_mfma_f32_16x16x32_f16 v[82:85], v[144:147], v[202:205], v[82:85]
	v_mfma_f32_16x16x32_f16 v[126:129], v[140:143], v[156:159], v[126:129]
	v_mfma_f32_16x16x32_f16 v[122:125], v[148:151], v[156:159], v[122:125]
	v_mfma_f32_16x16x32_f16 v[118:121], v[140:143], v[190:193], v[118:121]
	v_mfma_f32_16x16x32_f16 v[110:113], v[148:151], v[190:193], v[110:113]
	v_mfma_f32_16x16x32_f16 v[102:105], v[140:143], v[198:201], v[102:105]
	v_mfma_f32_16x16x32_f16 v[98:101], v[148:151], v[198:201], v[98:101]
	v_mfma_f32_16x16x32_f16 v[86:89], v[140:143], v[206:209], v[86:89]
	v_mfma_f32_16x16x32_f16 v[82:85], v[148:151], v[206:209], v[82:85]
	s_barrier
	s_add_i32 s85, 0, 0x14000
	s_add_i32 s22, s84, s19
	ds_read_b128 v[210:213], v161 offset:16384
	ds_read_b128 v[234:237], v161 offset:17408
	s_mov_b32 m0, s22
	ds_read_b128 v[238:241], v161 offset:18432
	global_load_lds_dwordx4 v178, s[50:51]
	s_add_i32 m0, s22, 0x2000
	ds_read_b128 v[242:245], v161 offset:19456
	global_load_lds_dwordx4 v174, s[50:51]
	s_barrier
	s_waitcnt lgkmcnt(0)
	s_waitcnt lgkmcnt(0)
	v_mfma_f32_16x16x32_f16 v[114:117], v[210:213], v[152:155], v[114:117]
	v_mfma_f32_16x16x32_f16 v[106:109], v[238:241], v[152:155], v[106:109]
	v_mfma_f32_16x16x32_f16 v[94:97], v[210:213], v[186:189], v[94:97]
	v_mfma_f32_16x16x32_f16 v[90:93], v[238:241], v[186:189], v[90:93]
	v_mfma_f32_16x16x32_f16 v[78:81], v[210:213], v[194:197], v[78:81]
	v_mfma_f32_16x16x32_f16 v[74:77], v[238:241], v[194:197], v[74:77]
	v_mfma_f32_16x16x32_f16 v[70:73], v[210:213], v[202:205], v[70:73]
	v_mfma_f32_16x16x32_f16 v[66:69], v[238:241], v[202:205], v[66:69]
	v_mfma_f32_16x16x32_f16 v[114:117], v[234:237], v[156:159], v[114:117]
	v_mfma_f32_16x16x32_f16 v[106:109], v[242:245], v[156:159], v[106:109]
	v_mfma_f32_16x16x32_f16 v[94:97], v[234:237], v[190:193], v[94:97]
	v_mfma_f32_16x16x32_f16 v[90:93], v[242:245], v[190:193], v[90:93]
	v_mfma_f32_16x16x32_f16 v[78:81], v[234:237], v[198:201], v[78:81]
	v_mfma_f32_16x16x32_f16 v[74:77], v[242:245], v[198:201], v[74:77]
	v_mfma_f32_16x16x32_f16 v[70:73], v[234:237], v[206:209], v[70:73]
	v_mfma_f32_16x16x32_f16 v[66:69], v[242:245], v[206:209], v[66:69]
	s_mov_b32 m0, s28
	s_barrier
	ds_read_b128 v[152:155], v222 offset:16384
	ds_read_b128 v[156:159], v222 offset:17408
	ds_read_b128 v[186:189], v222 offset:18432
	ds_read_b128 v[190:193], v222 offset:19456
	ds_read_b128 v[194:197], v222 offset:20480
	ds_read_b128 v[198:201], v222 offset:21504
	ds_read_b128 v[202:205], v222 offset:22528
	global_load_lds_dwordx4 v180, s[52:53]
	s_mov_b32 m0, s29
	ds_read_b128 v[206:209], v222 offset:23552
	global_load_lds_dwordx4 v176, s[52:53]
	s_barrier
	s_waitcnt lgkmcnt(0)
	s_waitcnt lgkmcnt(0)
	v_mfma_f32_16x16x32_f16 v[62:65], v[136:139], v[152:155], v[62:65]
	v_mfma_f32_16x16x32_f16 v[58:61], v[144:147], v[152:155], v[58:61]
	v_mfma_f32_16x16x32_f16 v[54:57], v[136:139], v[186:189], v[54:57]
	v_mfma_f32_16x16x32_f16 v[50:53], v[144:147], v[186:189], v[50:53]
	v_mfma_f32_16x16x32_f16 v[38:41], v[136:139], v[194:197], v[38:41]
	v_mfma_f32_16x16x32_f16 v[30:33], v[144:147], v[194:197], v[30:33]
	v_mfma_f32_16x16x32_f16 v[22:25], v[136:139], v[202:205], v[22:25]
	v_mfma_f32_16x16x32_f16 v[18:21], v[144:147], v[202:205], v[18:21]
	v_mfma_f32_16x16x32_f16 v[62:65], v[140:143], v[156:159], v[62:65]
	v_mfma_f32_16x16x32_f16 v[58:61], v[148:151], v[156:159], v[58:61]
	v_mfma_f32_16x16x32_f16 v[54:57], v[140:143], v[190:193], v[54:57]
	v_mfma_f32_16x16x32_f16 v[50:53], v[148:151], v[190:193], v[50:53]
	v_mfma_f32_16x16x32_f16 v[38:41], v[140:143], v[198:201], v[38:41]
	v_mfma_f32_16x16x32_f16 v[30:33], v[148:151], v[198:201], v[30:33]
	v_mfma_f32_16x16x32_f16 v[22:25], v[140:143], v[206:209], v[22:25]
	v_mfma_f32_16x16x32_f16 v[18:21], v[148:151], v[206:209], v[18:21]
	s_barrier
	s_add_u32 s22, s50, 0x80000
	s_addc_u32 s23, s51, 0
	s_add_i32 s84, s85, s19
	s_mov_b32 m0, s84
	s_nop 0
	global_load_lds_dwordx4 v178, s[22:23]
	s_add_i32 m0, s84, 0x2000
	s_nop 0
	global_load_lds_dwordx4 v174, s[22:23]
	s_waitcnt vmcnt(6)
	s_barrier
; #define PG8_STAGE(bufoff, gbase, voff) do { _Pragma("unroll") for (int _i = 0; _i < 2; ++_i) \
;         __builtin_amdgcn_global_load_lds((const unsigned*)((const char*)(gbase) + (voff)[_i]), (LAS unsigned*)(lds + (bufoff) + ldsw + _i * 8192), 16, 0, 0); } while (0)
; #define PG8_LDA(dst, b, h) do { _Pragma("unroll") for (int m = 0; m < 4; ++m) _Pragma("unroll") for (int k = 0; k < 2; ++k) dst[m][k] = *(const LAS f16x8*)(lds + PG8_SA(b, h) + aoff + m * 2048 + k * 1024); } while (0)
; #define PG8_LDB(dst, b, h) do { _Pragma("unroll") for (int n = 0; n < 2; ++n) _Pragma("unroll") for (int k = 0; k < 2; ++k) dst[n][k] = *(const LAS f16x8*)(lds + PG8_SB(b, h) + boff + n * 2048 + k * 1024); } while (0)
; #define PG8_MMA(ai, bj, At, Bt) do { __builtin_amdgcn_s_setprio(1); _Pragma("unroll") for (int m = 0; m < 4; ++m) _Pragma("unroll") for (int n = 0; n < 2; ++n) _Pragma("unroll") for (int k = 0; k < 2; ++k) \
;         acc[ai][bj][m][n] = __builtin_amdgcn_mfma_f32_16x16x32_f16(Bt[n][k], At[m][k], acc[ai][bj][m][n], 0, 0, 0); __builtin_amdgcn_s_setprio(0); } while (0)
; #define PG8_WAIT_V(n) asm volatile("s_waitcnt vmcnt(" #n ")" ::: "memory")
; #define PG8_WAIT_L(n) asm volatile("s_waitcnt lgkmcnt(" #n ")" ::: "memory")
; #define PG8_BAR __builtin_amdgcn_s_barrier()
; #define PG8_SCHED __builtin_amdgcn_sched_barrier(0)
; template <class Epi>
; __device__ __forceinline__ void gemm_phase(LAS unsigned char* lds, const Gemm g0, const StaticOrder& S, const Epi& E) {
;     ...
;             PG8_WAIT_V(6); PG8_BAR; PG8_MMA(1, 1, At, B1); PG8_BAR;
;             PG8_LDB(B0, 1, 0); PG8_SCHED; PG8_LDA(At, 1, 0); PG8_STAGE(PG8_SA(0, 1), a2 + hstep, voffA);
;             PG8_WAIT_L(8); PG8_BAR; PG8_WAIT_L(0); PG8_MMA(0, 0, At, B0); PG8_BAR; PG8_SCHED;
;             PG8_LDB(B1, 1, 1); PG8_STAGE(PG8_SB(1, 0), b3, voffB);
;             PG8_BAR; PG8_WAIT_L(0); PG8_MMA(0, 1, At, B1); PG8_BAR;
	v_mfma_f32_16x16x32_f16 v[46:49], v[210:213], v[152:155], v[46:49]
	v_mfma_f32_16x16x32_f16 v[42:45], v[238:241], v[152:155], v[42:45]
	v_mfma_f32_16x16x32_f16 v[34:37], v[210:213], v[186:189], v[34:37]
	v_mfma_f32_16x16x32_f16 v[26:29], v[238:241], v[186:189], v[26:29]
	v_mfma_f32_16x16x32_f16 v[14:17], v[210:213], v[194:197], v[14:17]
	v_mfma_f32_16x16x32_f16 v[10:13], v[238:241], v[194:197], v[10:13]
	v_mfma_f32_16x16x32_f16 v[6:9], v[210:213], v[202:205], v[6:9]
	v_mfma_f32_16x16x32_f16 v[2:5], v[238:241], v[202:205], v[2:5]
	v_mfma_f32_16x16x32_f16 v[46:49], v[234:237], v[156:159], v[46:49]
	v_mfma_f32_16x16x32_f16 v[42:45], v[242:245], v[156:159], v[42:45]
	v_mfma_f32_16x16x32_f16 v[34:37], v[234:237], v[190:193], v[34:37]
	v_mfma_f32_16x16x32_f16 v[26:29], v[242:245], v[190:193], v[26:29]
	v_mfma_f32_16x16x32_f16 v[14:17], v[234:237], v[198:201], v[14:17]
	v_mfma_f32_16x16x32_f16 v[10:13], v[242:245], v[198:201], v[10:13]
	v_mfma_f32_16x16x32_f16 v[6:9], v[234:237], v[206:209], v[6:9]
	v_mfma_f32_16x16x32_f16 v[2:5], v[242:245], v[206:209], v[2:5]
	s_add_i32 s84, 0, 0x18000
	s_barrier
	ds_read_b128 v[136:139], v161 offset:32768
	ds_read_b128 v[140:143], v161 offset:33792
	ds_read_b128 v[144:147], v161 offset:34816
	ds_read_b128 v[148:151], v161 offset:35840
	s_add_u32 s22, s52, 0x80000
	s_addc_u32 s23, s53, 0
	s_mov_b32 m0, s31
	ds_read_b128 v[152:155], v222 offset:32768
	ds_read_b128 v[156:159], v222 offset:33792
	ds_read_b128 v[186:189], v222 offset:34816
	ds_read_b128 v[190:193], v222 offset:35840
	ds_read_b128 v[194:197], v222 offset:36864
	ds_read_b128 v[198:201], v222 offset:37888
	ds_read_b128 v[202:205], v222 offset:38912
	global_load_lds_dwordx4 v180, s[22:23]
	s_mov_b32 m0, s58
	ds_read_b128 v[206:209], v222 offset:39936
	global_load_lds_dwordx4 v176, s[22:23]
	s_waitcnt lgkmcnt(8)
	s_barrier
	s_waitcnt lgkmcnt(0)
	s_waitcnt lgkmcnt(0)
	v_mfma_f32_16x16x32_f16 v[126:129], v[136:139], v[152:155], v[126:129]
	v_mfma_f32_16x16x32_f16 v[122:125], v[144:147], v[152:155], v[122:125]
	v_mfma_f32_16x16x32_f16 v[118:121], v[136:139], v[186:189], v[118:121]
	v_mfma_f32_16x16x32_f16 v[110:113], v[144:147], v[186:189], v[110:113]
	v_mfma_f32_16x16x32_f16 v[102:105], v[136:139], v[194:197], v[102:105]
	v_mfma_f32_16x16x32_f16 v[98:101], v[144:147], v[194:197], v[98:101]
	v_mfma_f32_16x16x32_f16 v[86:89], v[136:139], v[202:205], v[86:89]
	v_mfma_f32_16x16x32_f16 v[82:85], v[144:147], v[202:205], v[82:85]
	v_mfma_f32_16x16x32_f16 v[126:129], v[140:143], v[156:159], v[126:129]
	v_mfma_f32_16x16x32_f16 v[122:125], v[148:151], v[156:159], v[122:125]
	v_mfma_f32_16x16x32_f16 v[118:121], v[140:143], v[190:193], v[118:121]
	v_mfma_f32_16x16x32_f16 v[110:113], v[148:151], v[190:193], v[110:113]
	v_mfma_f32_16x16x32_f16 v[102:105], v[140:143], v[198:201], v[102:105]
	v_mfma_f32_16x16x32_f16 v[98:101], v[148:151], v[198:201], v[98:101]
	v_mfma_f32_16x16x32_f16 v[86:89], v[140:143], v[206:209], v[86:89]
	v_mfma_f32_16x16x32_f16 v[82:85], v[148:151], v[206:209], v[82:85]
	s_barrier
	s_add_i32 s85, 0, 0x1c000
	s_add_i32 s22, s84, s19
	s_mov_b32 m0, s22
	ds_read_b128 v[210:213], v161 offset:49152
	ds_read_b128 v[234:237], v161 offset:50176
	ds_read_b128 v[238:241], v161 offset:51200
	global_load_lds_dwordx4 v160, s[50:51]
	s_add_i32 m0, s22, 0x2000
	ds_read_b128 v[242:245], v161 offset:52224
	global_load_lds_dwordx4 v162, s[50:51]
	s_barrier
; #define PG8_STAGE(bufoff, gbase, voff) do { _Pragma("unroll") for (int _i = 0; _i < 2; ++_i) \
;         __builtin_amdgcn_global_load_lds((const unsigned*)((const char*)(gbase) + (voff)[_i]), (LAS unsigned*)(lds + (bufoff) + ldsw + _i * 8192), 16, 0, 0); } while (0)
; #define PG8_LDA(dst, b, h) do { _Pragma("unroll") for (int m = 0; m < 4; ++m) _Pragma("unroll") for (int k = 0; k < 2; ++k) dst[m][k] = *(const LAS f16x8*)(lds + PG8_SA(b, h) + aoff + m * 2048 + k * 1024); } while (0)
; #define PG8_MMA(ai, bj, At, Bt) do { __builtin_amdgcn_s_setprio(1); _Pragma("unroll") for (int m = 0; m < 4; ++m) _Pragma("unroll") for (int n = 0; n < 2; ++n) _Pragma("unroll") for (int k = 0; k < 2; ++k) \
;         acc[ai][bj][m][n] = __builtin_amdgcn_mfma_f32_16x16x32_f16(Bt[n][k], At[m][k], acc[ai][bj][m][n], 0, 0, 0); __builtin_amdgcn_s_setprio(0); } while (0)
; #define PG8_WAIT_V(n) asm volatile("s_waitcnt vmcnt(" #n ")" ::: "memory")
; #define PG8_WAIT_L(n) asm volatile("s_waitcnt lgkmcnt(" #n ")" ::: "memory")
; #define PG8_BAR __builtin_amdgcn_s_barrier()
; #define PG8_SCHED __builtin_amdgcn_sched_barrier(0)
; template <class Epi>
; __device__ __forceinline__ void gemm_phase(LAS unsigned char* lds, const Gemm g0, const StaticOrder& S, const Epi& E) {
;     ...
;             PG8_BAR; PG8_WAIT_L(0); PG8_MMA(0, 1, At, B1); PG8_BAR;
;             PG8_LDA(At, 1, 1); PG8_STAGE(PG8_SA(1, 0), a3, voffA);
;             PG8_BAR; PG8_WAIT_L(0); PG8_MMA(1, 0, At, B0); PG8_BAR; PG8_SCHED;
;             PG8_STAGE(PG8_SB(1, 1), b3 + hstep, voffB);
;             PG8_WAIT_V(6); PG8_BAR; PG8_MMA(1, 1, At, B1); PG8_BAR;
	s_waitcnt lgkmcnt(0)
	s_waitcnt lgkmcnt(0)
	v_mfma_f32_16x16x32_f16 v[114:117], v[210:213], v[152:155], v[114:117]
	v_mfma_f32_16x16x32_f16 v[106:109], v[238:241], v[152:155], v[106:109]
	v_mfma_f32_16x16x32_f16 v[94:97], v[210:213], v[186:189], v[94:97]
	v_mfma_f32_16x16x32_f16 v[90:93], v[238:241], v[186:189], v[90:93]
	v_mfma_f32_16x16x32_f16 v[78:81], v[210:213], v[194:197], v[78:81]
	v_mfma_f32_16x16x32_f16 v[74:77], v[238:241], v[194:197], v[74:77]
	v_mfma_f32_16x16x32_f16 v[70:73], v[210:213], v[202:205], v[70:73]
	v_mfma_f32_16x16x32_f16 v[66:69], v[238:241], v[202:205], v[66:69]
	v_mfma_f32_16x16x32_f16 v[114:117], v[234:237], v[156:159], v[114:117]
	v_mfma_f32_16x16x32_f16 v[106:109], v[242:245], v[156:159], v[106:109]
	v_mfma_f32_16x16x32_f16 v[94:97], v[234:237], v[190:193], v[94:97]
	v_mfma_f32_16x16x32_f16 v[90:93], v[242:245], v[190:193], v[90:93]
	v_mfma_f32_16x16x32_f16 v[78:81], v[234:237], v[198:201], v[78:81]
	v_mfma_f32_16x16x32_f16 v[74:77], v[242:245], v[198:201], v[74:77]
	v_mfma_f32_16x16x32_f16 v[70:73], v[234:237], v[206:209], v[70:73]
	v_mfma_f32_16x16x32_f16 v[66:69], v[242:245], v[206:209], v[66:69]
	s_mov_b32 m0, s59
	s_barrier
	ds_read_b128 v[152:155], v222 offset:49152
	ds_read_b128 v[156:159], v222 offset:50176
	ds_read_b128 v[186:189], v222 offset:51200
	ds_read_b128 v[190:193], v222 offset:52224
	ds_read_b128 v[194:197], v222 offset:53248
	ds_read_b128 v[198:201], v222 offset:54272
	ds_read_b128 v[202:205], v222 offset:55296
	global_load_lds_dwordx4 v164, s[52:53]
	s_mov_b32 m0, s61
	ds_read_b128 v[206:209], v222 offset:56320
	global_load_lds_dwordx4 v170, s[52:53]
	s_barrier
	s_waitcnt lgkmcnt(0)
	s_waitcnt lgkmcnt(0)
	v_mfma_f32_16x16x32_f16 v[62:65], v[136:139], v[152:155], v[62:65]
	v_mfma_f32_16x16x32_f16 v[58:61], v[144:147], v[152:155], v[58:61]
	v_mfma_f32_16x16x32_f16 v[54:57], v[136:139], v[186:189], v[54:57]
	v_mfma_f32_16x16x32_f16 v[50:53], v[144:147], v[186:189], v[50:53]
	v_mfma_f32_16x16x32_f16 v[38:41], v[136:139], v[194:197], v[38:41]
	v_mfma_f32_16x16x32_f16 v[30:33], v[144:147], v[194:197], v[30:33]
	v_mfma_f32_16x16x32_f16 v[22:25], v[136:139], v[202:205], v[22:25]
	v_mfma_f32_16x16x32_f16 v[18:21], v[144:147], v[202:205], v[18:21]
	v_mfma_f32_16x16x32_f16 v[62:65], v[140:143], v[156:159], v[62:65]
	v_mfma_f32_16x16x32_f16 v[58:61], v[148:151], v[156:159], v[58:61]
	v_mfma_f32_16x16x32_f16 v[54:57], v[140:143], v[190:193], v[54:57]
	v_mfma_f32_16x16x32_f16 v[50:53], v[148:151], v[190:193], v[50:53]
	v_mfma_f32_16x16x32_f16 v[38:41], v[140:143], v[198:201], v[38:41]
	v_mfma_f32_16x16x32_f16 v[30:33], v[148:151], v[198:201], v[30:33]
	v_mfma_f32_16x16x32_f16 v[22:25], v[140:143], v[206:209], v[22:25]
	v_mfma_f32_16x16x32_f16 v[18:21], v[148:151], v[206:209], v[18:21]
	s_barrier
	s_add_u32 s22, s50, 0x80080
	s_addc_u32 s23, s51, 0
	s_add_i32 s50, s85, s19
	s_mov_b32 m0, s50
	s_nop 0
	global_load_lds_dwordx4 v178, s[22:23]
	s_add_i32 m0, s50, 0x2000
	s_nop 0
	global_load_lds_dwordx4 v174, s[22:23]
	s_waitcnt vmcnt(6)
	s_barrier
	v_mfma_f32_16x16x32_f16 v[46:49], v[210:213], v[152:155], v[46:49]
	v_mfma_f32_16x16x32_f16 v[42:45], v[238:241], v[152:155], v[42:45]
	v_mfma_f32_16x16x32_f16 v[34:37], v[210:213], v[186:189], v[34:37]
	v_mfma_f32_16x16x32_f16 v[26:29], v[238:241], v[186:189], v[26:29]
	v_mfma_f32_16x16x32_f16 v[14:17], v[210:213], v[194:197], v[14:17]
	v_mfma_f32_16x16x32_f16 v[10:13], v[238:241], v[194:197], v[10:13]
	v_mfma_f32_16x16x32_f16 v[6:9], v[210:213], v[202:205], v[6:9]
	v_mfma_f32_16x16x32_f16 v[2:5], v[238:241], v[202:205], v[2:5]
	v_mfma_f32_16x16x32_f16 v[46:49], v[234:237], v[156:159], v[46:49]
	v_mfma_f32_16x16x32_f16 v[42:45], v[242:245], v[156:159], v[42:45]
	v_mfma_f32_16x16x32_f16 v[34:37], v[234:237], v[190:193], v[34:37]
	v_mfma_f32_16x16x32_f16 v[26:29], v[242:245], v[190:193], v[26:29]
	v_mfma_f32_16x16x32_f16 v[14:17], v[234:237], v[198:201], v[14:17]
	v_mfma_f32_16x16x32_f16 v[10:13], v[242:245], v[198:201], v[10:13]
	v_mfma_f32_16x16x32_f16 v[6:9], v[234:237], v[206:209], v[6:9]
	v_mfma_f32_16x16x32_f16 v[2:5], v[242:245], v[206:209], v[2:5]
	s_add_i32 s83, s83, 2
	s_add_u32 s24, s24, 0x100
	s_addc_u32 s25, s25, 0
	s_add_u32 s0, s0, 0x100
	s_addc_u32 s1, s1, 0
	s_cmp_gt_u32 s83, 29
	s_barrier
	s_cbranch_scc1 .LBB0_201

; #define PG8_STAGE(bufoff, gbase, voff) do { _Pragma("unroll") for (int _i = 0; _i < 2; ++_i) \
;         __builtin_amdgcn_global_load_lds((const unsigned*)((const char*)(gbase) + (voff)[_i]), (LAS unsigned*)(lds + (bufoff) + ldsw + _i * 8192), 16, 0, 0); } while (0)
; #define PG8_LDA(dst, b, h) do { _Pragma("unroll") for (int m = 0; m < 4; ++m) _Pragma("unroll") for (int k = 0; k < 2; ++k) dst[m][k] = *(const LAS f16x8*)(lds + PG8_SA(b, h) + aoff + m * 2048 + k * 1024); } while (0)
; #define PG8_LDB(dst, b, h) do { _Pragma("unroll") for (int n = 0; n < 2; ++n) _Pragma("unroll") for (int k = 0; k < 2; ++k) dst[n][k] = *(const LAS f16x8*)(lds + PG8_SB(b, h) + boff + n * 2048 + k * 1024); } while (0)
; #define PG8_MMA(ai, bj, At, Bt) do { __builtin_amdgcn_s_setprio(1); _Pragma("unroll") for (int m = 0; m < 4; ++m) _Pragma("unroll") for (int n = 0; n < 2; ++n) _Pragma("unroll") for (int k = 0; k < 2; ++k) \
;         acc[ai][bj][m][n] = __builtin_amdgcn_mfma_f32_16x16x32_f16(Bt[n][k], At[m][k], acc[ai][bj][m][n], 0, 0, 0); __builtin_amdgcn_s_setprio(0); } while (0)
; #define PG8_WAIT_V(n) asm volatile("s_waitcnt vmcnt(" #n ")" ::: "memory")
; #define PG8_WAIT_L(n) asm volatile("s_waitcnt lgkmcnt(" #n ")" ::: "memory")
; #define PG8_BAR __builtin_amdgcn_s_barrier()
; #define PG8_SCHED __builtin_amdgcn_sched_barrier(0)
; template <class Epi>
; __device__ __forceinline__ void gemm_phase(LAS unsigned char* lds, const Gemm g0, const StaticOrder& S, const Epi& E) {
;     ...
;             PG8_LDB(B0, 0, 0); PG8_SCHED; PG8_LDA(At, 0, 0); PG8_STAGE(PG8_SA(1, 1), a1 + hstep, voffA);
;             PG8_WAIT_L(8); PG8_BAR; PG8_WAIT_L(0); PG8_MMA(0, 0, At, B0); PG8_BAR; PG8_SCHED;
;             PG8_LDB(B1, 0, 1); PG8_STAGE(PG8_SB(0, 0), b2, voffB);
;             PG8_BAR; PG8_WAIT_L(0); PG8_MMA(0, 1, At, B1); PG8_BAR;
;             PG8_LDA(At, 0, 1); PG8_STAGE(PG8_SA(0, 0), a2, voffA);
;             PG8_BAR; PG8_WAIT_L(0); PG8_MMA(1, 0, At, B0); PG8_BAR; PG8_SCHED;
;             PG8_STAGE(PG8_SB(0, 1), b2 + hstep, voffB);
;             PG8_WAIT_V(6); PG8_BAR; PG8_MMA(1, 1, At, B1); PG8_BAR;
.LBB0_302:
	s_add_u32 s22, s6, 0xfff80080
	s_addc_u32 s23, s7, -1
	s_add_i32 s59, 0, 0x10000
	ds_read_b128 v[142:145], v161
	ds_read_b128 v[152:155], v161 offset:1024
	ds_read_b128 v[156:159], v161 offset:2048
	ds_read_b128 v[174:177], v161 offset:3072
	s_cmp_eq_u32 s58, 28
	s_cselect_b32 s37, s15, s23
	s_cselect_b32 s36, s52, s22
	s_cselect_b32 s35, s13, s53
	s_cselect_b32 s34, s24, s25
	s_add_i32 m0, s28, 0xc000
	ds_read_b128 v[178:181], v150
	ds_read_b128 v[182:185], v150 offset:1024
	ds_read_b128 v[186:189], v150 offset:2048
	ds_read_b128 v[190:193], v150 offset:3072
	ds_read_b128 v[194:197], v150 offset:4096
	ds_read_b128 v[198:201], v150 offset:5120
	ds_read_b128 v[202:205], v150 offset:6144
	global_load_lds_dwordx4 v140, s[6:7]
	s_add_i32 m0, s28, 0xe000
	ds_read_b128 v[206:209], v150 offset:7168
	global_load_lds_dwordx4 v138, s[6:7]
	s_waitcnt lgkmcnt(8)
	s_barrier
	s_waitcnt lgkmcnt(0)
	s_waitcnt lgkmcnt(0)
	v_mfma_f32_16x16x32_f16 v[126:129], v[142:145], v[178:181], v[126:129]
	v_mfma_f32_16x16x32_f16 v[122:125], v[156:159], v[178:181], v[122:125]
	v_mfma_f32_16x16x32_f16 v[110:113], v[142:145], v[186:189], v[110:113]
	v_mfma_f32_16x16x32_f16 v[106:109], v[156:159], v[186:189], v[106:109]
	v_mfma_f32_16x16x32_f16 v[94:97], v[142:145], v[194:197], v[94:97]
	v_mfma_f32_16x16x32_f16 v[90:93], v[156:159], v[194:197], v[90:93]
	v_mfma_f32_16x16x32_f16 v[78:81], v[142:145], v[202:205], v[78:81]
	v_mfma_f32_16x16x32_f16 v[74:77], v[156:159], v[202:205], v[74:77]
	v_mfma_f32_16x16x32_f16 v[126:129], v[152:155], v[182:185], v[126:129]
	v_mfma_f32_16x16x32_f16 v[122:125], v[174:177], v[182:185], v[122:125]
	v_mfma_f32_16x16x32_f16 v[110:113], v[152:155], v[190:193], v[110:113]
	v_mfma_f32_16x16x32_f16 v[106:109], v[174:177], v[190:193], v[106:109]
	v_mfma_f32_16x16x32_f16 v[94:97], v[152:155], v[198:201], v[94:97]
	v_mfma_f32_16x16x32_f16 v[90:93], v[174:177], v[198:201], v[90:93]
	v_mfma_f32_16x16x32_f16 v[78:81], v[152:155], v[206:209], v[78:81]
	v_mfma_f32_16x16x32_f16 v[74:77], v[174:177], v[206:209], v[74:77]
	s_barrier
	s_add_i32 s61, 0, 0x14000
	s_add_i32 s22, s59, s19
	ds_read_b128 v[210:213], v161 offset:16384
	ds_read_b128 v[234:237], v161 offset:17408
	s_mov_b32 m0, s22
	ds_read_b128 v[238:241], v161 offset:18432
	global_load_lds_dwordx4 v134, s[34:35]
	s_add_i32 m0, s22, 0x2000
	ds_read_b128 v[242:245], v161 offset:19456
	global_load_lds_dwordx4 v130, s[34:35]
	s_barrier
	s_waitcnt lgkmcnt(0)
	s_waitcnt lgkmcnt(0)
	v_mfma_f32_16x16x32_f16 v[118:121], v[210:213], v[178:181], v[118:121]
	v_mfma_f32_16x16x32_f16 v[114:117], v[238:241], v[178:181], v[114:117]
	v_mfma_f32_16x16x32_f16 v[102:105], v[210:213], v[186:189], v[102:105]
	v_mfma_f32_16x16x32_f16 v[98:101], v[238:241], v[186:189], v[98:101]
	v_mfma_f32_16x16x32_f16 v[86:89], v[210:213], v[194:197], v[86:89]
	v_mfma_f32_16x16x32_f16 v[82:85], v[238:241], v[194:197], v[82:85]
	v_mfma_f32_16x16x32_f16 v[70:73], v[210:213], v[202:205], v[70:73]
	v_mfma_f32_16x16x32_f16 v[66:69], v[238:241], v[202:205], v[66:69]
	v_mfma_f32_16x16x32_f16 v[118:121], v[234:237], v[182:185], v[118:121]
	v_mfma_f32_16x16x32_f16 v[114:117], v[242:245], v[182:185], v[114:117]
	v_mfma_f32_16x16x32_f16 v[102:105], v[234:237], v[190:193], v[102:105]
	v_mfma_f32_16x16x32_f16 v[98:101], v[242:245], v[190:193], v[98:101]
	v_mfma_f32_16x16x32_f16 v[86:89], v[234:237], v[198:201], v[86:89]
	v_mfma_f32_16x16x32_f16 v[82:85], v[242:245], v[198:201], v[82:85]
	v_mfma_f32_16x16x32_f16 v[70:73], v[234:237], v[206:209], v[70:73]
	v_mfma_f32_16x16x32_f16 v[66:69], v[242:245], v[206:209], v[66:69]
	s_mov_b32 m0, s28
	s_barrier
	ds_read_b128 v[178:181], v150 offset:16384
	ds_read_b128 v[182:185], v150 offset:17408
	ds_read_b128 v[186:189], v150 offset:18432
	ds_read_b128 v[190:193], v150 offset:19456
	ds_read_b128 v[194:197], v150 offset:20480
	ds_read_b128 v[198:201], v150 offset:21504
	ds_read_b128 v[202:205], v150 offset:22528
	global_load_lds_dwordx4 v136, s[36:37]
	s_mov_b32 m0, s29
	ds_read_b128 v[206:209], v150 offset:23552
	global_load_lds_dwordx4 v132, s[36:37]
	s_barrier
	s_waitcnt lgkmcnt(0)
	s_waitcnt lgkmcnt(0)
	v_mfma_f32_16x16x32_f16 v[62:65], v[142:145], v[178:181], v[62:65]
	v_mfma_f32_16x16x32_f16 v[58:61], v[156:159], v[178:181], v[58:61]
	v_mfma_f32_16x16x32_f16 v[46:49], v[142:145], v[186:189], v[46:49]
	v_mfma_f32_16x16x32_f16 v[42:45], v[156:159], v[186:189], v[42:45]
	v_mfma_f32_16x16x32_f16 v[30:33], v[142:145], v[194:197], v[30:33]
	v_mfma_f32_16x16x32_f16 v[26:29], v[156:159], v[194:197], v[26:29]
	v_mfma_f32_16x16x32_f16 v[14:17], v[142:145], v[202:205], v[14:17]
	v_mfma_f32_16x16x32_f16 v[10:13], v[156:159], v[202:205], v[10:13]
	v_mfma_f32_16x16x32_f16 v[62:65], v[152:155], v[182:185], v[62:65]
	v_mfma_f32_16x16x32_f16 v[58:61], v[174:177], v[182:185], v[58:61]
	v_mfma_f32_16x16x32_f16 v[46:49], v[152:155], v[190:193], v[46:49]
	v_mfma_f32_16x16x32_f16 v[42:45], v[174:177], v[190:193], v[42:45]
	v_mfma_f32_16x16x32_f16 v[30:33], v[152:155], v[198:201], v[30:33]
	v_mfma_f32_16x16x32_f16 v[26:29], v[174:177], v[198:201], v[26:29]
	v_mfma_f32_16x16x32_f16 v[14:17], v[152:155], v[206:209], v[14:17]
	v_mfma_f32_16x16x32_f16 v[10:13], v[174:177], v[206:209], v[10:13]
	s_barrier
	s_add_u32 s22, s34, 0x80000
	s_addc_u32 s23, s35, 0
	s_add_i32 s59, s61, s19
	s_mov_b32 m0, s59
	s_nop 0
	global_load_lds_dwordx4 v134, s[22:23]
	s_add_i32 m0, s59, 0x2000
	s_nop 0
	global_load_lds_dwordx4 v130, s[22:23]
	s_waitcnt vmcnt(6)
	s_barrier
; #define PG8_STAGE(bufoff, gbase, voff) do { _Pragma("unroll") for (int _i = 0; _i < 2; ++_i) \
;         __builtin_amdgcn_global_load_lds((const unsigned*)((const char*)(gbase) + (voff)[_i]), (LAS unsigned*)(lds + (bufoff) + ldsw + _i * 8192), 16, 0, 0); } while (0)
; #define PG8_LDA(dst, b, h) do { _Pragma("unroll") for (int m = 0; m < 4; ++m) _Pragma("unroll") for (int k = 0; k < 2; ++k) dst[m][k] = *(const LAS f16x8*)(lds + PG8_SA(b, h) + aoff + m * 2048 + k * 1024); } while (0)
; #define PG8_LDB(dst, b, h) do { _Pragma("unroll") for (int n = 0; n < 2; ++n) _Pragma("unroll") for (int k = 0; k < 2; ++k) dst[n][k] = *(const LAS f16x8*)(lds + PG8_SB(b, h) + boff + n * 2048 + k * 1024); } while (0)
; #define PG8_MMA(ai, bj, At, Bt) do { __builtin_amdgcn_s_setprio(1); _Pragma("unroll") for (int m = 0; m < 4; ++m) _Pragma("unroll") for (int n = 0; n < 2; ++n) _Pragma("unroll") for (int k = 0; k < 2; ++k) \
;         acc[ai][bj][m][n] = __builtin_amdgcn_mfma_f32_16x16x32_f16(Bt[n][k], At[m][k], acc[ai][bj][m][n], 0, 0, 0); __builtin_amdgcn_s_setprio(0); } while (0)
; #define PG8_WAIT_V(n) asm volatile("s_waitcnt vmcnt(" #n ")" ::: "memory")
; #define PG8_WAIT_L(n) asm volatile("s_waitcnt lgkmcnt(" #n ")" ::: "memory")
; #define PG8_BAR __builtin_amdgcn_s_barrier()
; #define PG8_SCHED __builtin_amdgcn_sched_barrier(0)
; template <class Epi>
; __device__ __forceinline__ void gemm_phase(LAS unsigned char* lds, const Gemm g0, const StaticOrder& S, const Epi& E) {
;     ...
;             PG8_WAIT_V(6); PG8_BAR; PG8_MMA(1, 1, At, B1); PG8_BAR;
;             PG8_LDB(B0, 1, 0); PG8_SCHED; PG8_LDA(At, 1, 0); PG8_STAGE(PG8_SA(0, 1), a2 + hstep, voffA);
;             PG8_WAIT_L(8); PG8_BAR; PG8_WAIT_L(0); PG8_MMA(0, 0, At, B0); PG8_BAR; PG8_SCHED;
;             PG8_LDB(B1, 1, 1); PG8_STAGE(PG8_SB(1, 0), b3, voffB);
;             PG8_BAR; PG8_WAIT_L(0); PG8_MMA(0, 1, At, B1); PG8_BAR;
;             PG8_LDA(At, 1, 1); PG8_STAGE(PG8_SA(1, 0), a3, voffA);
	v_mfma_f32_16x16x32_f16 v[54:57], v[210:213], v[178:181], v[54:57]
	v_mfma_f32_16x16x32_f16 v[50:53], v[238:241], v[178:181], v[50:53]
	v_mfma_f32_16x16x32_f16 v[38:41], v[210:213], v[186:189], v[38:41]
	v_mfma_f32_16x16x32_f16 v[34:37], v[238:241], v[186:189], v[34:37]
	v_mfma_f32_16x16x32_f16 v[22:25], v[210:213], v[194:197], v[22:25]
	v_mfma_f32_16x16x32_f16 v[18:21], v[238:241], v[194:197], v[18:21]
	v_mfma_f32_16x16x32_f16 v[6:9], v[210:213], v[202:205], v[6:9]
	v_mfma_f32_16x16x32_f16 v[2:5], v[238:241], v[202:205], v[2:5]
	v_mfma_f32_16x16x32_f16 v[54:57], v[234:237], v[182:185], v[54:57]
	v_mfma_f32_16x16x32_f16 v[50:53], v[242:245], v[182:185], v[50:53]
	v_mfma_f32_16x16x32_f16 v[38:41], v[234:237], v[190:193], v[38:41]
	v_mfma_f32_16x16x32_f16 v[34:37], v[242:245], v[190:193], v[34:37]
	v_mfma_f32_16x16x32_f16 v[22:25], v[234:237], v[198:201], v[22:25]
	v_mfma_f32_16x16x32_f16 v[18:21], v[242:245], v[198:201], v[18:21]
	v_mfma_f32_16x16x32_f16 v[6:9], v[234:237], v[206:209], v[6:9]
	v_mfma_f32_16x16x32_f16 v[2:5], v[242:245], v[206:209], v[2:5]
	s_add_i32 s59, 0, 0x18000
	s_barrier
	ds_read_b128 v[142:145], v161 offset:32768
	ds_read_b128 v[152:155], v161 offset:33792
	ds_read_b128 v[156:159], v161 offset:34816
	ds_read_b128 v[174:177], v161 offset:35840
	s_add_u32 s22, s36, 0x80000
	s_addc_u32 s23, s37, 0
	s_mov_b32 m0, s31
	ds_read_b128 v[178:181], v150 offset:32768
	ds_read_b128 v[182:185], v150 offset:33792
	ds_read_b128 v[186:189], v150 offset:34816
	ds_read_b128 v[190:193], v150 offset:35840
	ds_read_b128 v[194:197], v150 offset:36864
	ds_read_b128 v[198:201], v150 offset:37888
	ds_read_b128 v[202:205], v150 offset:38912
	global_load_lds_dwordx4 v136, s[22:23]
	s_mov_b32 m0, s38
	ds_read_b128 v[206:209], v150 offset:39936
	global_load_lds_dwordx4 v132, s[22:23]
	s_waitcnt lgkmcnt(8)
	s_barrier
	s_waitcnt lgkmcnt(0)
	s_waitcnt lgkmcnt(0)
	v_mfma_f32_16x16x32_f16 v[126:129], v[142:145], v[178:181], v[126:129]
	v_mfma_f32_16x16x32_f16 v[122:125], v[156:159], v[178:181], v[122:125]
	v_mfma_f32_16x16x32_f16 v[110:113], v[142:145], v[186:189], v[110:113]
	v_mfma_f32_16x16x32_f16 v[106:109], v[156:159], v[186:189], v[106:109]
	v_mfma_f32_16x16x32_f16 v[94:97], v[142:145], v[194:197], v[94:97]
	v_mfma_f32_16x16x32_f16 v[90:93], v[156:159], v[194:197], v[90:93]
	v_mfma_f32_16x16x32_f16 v[78:81], v[142:145], v[202:205], v[78:81]
	v_mfma_f32_16x16x32_f16 v[74:77], v[156:159], v[202:205], v[74:77]
	v_mfma_f32_16x16x32_f16 v[126:129], v[152:155], v[182:185], v[126:129]
	v_mfma_f32_16x16x32_f16 v[122:125], v[174:177], v[182:185], v[122:125]
	v_mfma_f32_16x16x32_f16 v[110:113], v[152:155], v[190:193], v[110:113]
	v_mfma_f32_16x16x32_f16 v[106:109], v[174:177], v[190:193], v[106:109]
	v_mfma_f32_16x16x32_f16 v[94:97], v[152:155], v[198:201], v[94:97]
	v_mfma_f32_16x16x32_f16 v[90:93], v[174:177], v[198:201], v[90:93]
	v_mfma_f32_16x16x32_f16 v[78:81], v[152:155], v[206:209], v[78:81]
	v_mfma_f32_16x16x32_f16 v[74:77], v[174:177], v[206:209], v[74:77]
	s_barrier
	s_add_i32 s61, 0, 0x1c000
	s_add_i32 s22, s59, s19
	s_mov_b32 m0, s22
	ds_read_b128 v[210:213], v161 offset:49152
	ds_read_b128 v[234:237], v161 offset:50176
	ds_read_b128 v[238:241], v161 offset:51200
	global_load_lds_dwordx4 v146, s[34:35]
	s_add_i32 m0, s22, 0x2000
	ds_read_b128 v[242:245], v161 offset:52224
	global_load_lds_dwordx4 v160, s[34:35]
	s_barrier
	s_waitcnt lgkmcnt(0)
	s_waitcnt lgkmcnt(0)
	v_mfma_f32_16x16x32_f16 v[118:121], v[210:213], v[178:181], v[118:121]
	v_mfma_f32_16x16x32_f16 v[114:117], v[238:241], v[178:181], v[114:117]
	v_mfma_f32_16x16x32_f16 v[102:105], v[210:213], v[186:189], v[102:105]
	v_mfma_f32_16x16x32_f16 v[98:101], v[238:241], v[186:189], v[98:101]
	v_mfma_f32_16x16x32_f16 v[86:89], v[210:213], v[194:197], v[86:89]
	v_mfma_f32_16x16x32_f16 v[82:85], v[238:241], v[194:197], v[82:85]
	v_mfma_f32_16x16x32_f16 v[70:73], v[210:213], v[202:205], v[70:73]
	v_mfma_f32_16x16x32_f16 v[66:69], v[238:241], v[202:205], v[66:69]
	v_mfma_f32_16x16x32_f16 v[118:121], v[234:237], v[182:185], v[118:121]
	v_mfma_f32_16x16x32_f16 v[114:117], v[242:245], v[182:185], v[114:117]
	v_mfma_f32_16x16x32_f16 v[102:105], v[234:237], v[190:193], v[102:105]
	v_mfma_f32_16x16x32_f16 v[98:101], v[242:245], v[190:193], v[98:101]
	v_mfma_f32_16x16x32_f16 v[86:89], v[234:237], v[198:201], v[86:89]
	v_mfma_f32_16x16x32_f16 v[82:85], v[242:245], v[198:201], v[82:85]
	v_mfma_f32_16x16x32_f16 v[70:73], v[234:237], v[206:209], v[70:73]
	v_mfma_f32_16x16x32_f16 v[66:69], v[242:245], v[206:209], v[66:69]
	s_mov_b32 m0, s39
	s_barrier
	ds_read_b128 v[178:181], v150 offset:49152
	ds_read_b128 v[182:185], v150 offset:50176
	ds_read_b128 v[186:189], v150 offset:51200
	ds_read_b128 v[190:193], v150 offset:52224
	ds_read_b128 v[194:197], v150 offset:53248
	ds_read_b128 v[198:201], v150 offset:54272
	ds_read_b128 v[202:205], v150 offset:55296
	global_load_lds_dwordx4 v162, s[36:37]
	s_mov_b32 m0, s48
	ds_read_b128 v[206:209], v150 offset:56320
	global_load_lds_dwordx4 v164, s[36:37]
	s_barrier
; __device__ __forceinline__ float gelu_tanh(float x) { const float y = 1.5957691216057308f * (x + 0.044715f * x * x * x); return x * fast_rcp(1.0f + __expf(-y)); }
; #define PG8_STAGE(bufoff, gbase, voff) do { _Pragma("unroll") for (int _i = 0; _i < 2; ++_i) \
;         __builtin_amdgcn_global_load_lds((const unsigned*)((const char*)(gbase) + (voff)[_i]), (LAS unsigned*)(lds + (bufoff) + ldsw + _i * 8192), 16, 0, 0); } while (0)
; #define PG8_MMA(ai, bj, At, Bt) do { __builtin_amdgcn_s_setprio(1); _Pragma("unroll") for (int m = 0; m < 4; ++m) _Pragma("unroll") for (int n = 0; n < 2; ++n) _Pragma("unroll") for (int k = 0; k < 2; ++k) \
;         acc[ai][bj][m][n] = __builtin_amdgcn_mfma_f32_16x16x32_f16(Bt[n][k], At[m][k], acc[ai][bj][m][n], 0, 0, 0); __builtin_amdgcn_s_setprio(0); } while (0)
; #define PG8_WAIT_V(n) asm volatile("s_waitcnt vmcnt(" #n ")" ::: "memory")
; #define PG8_WAIT_L(n) asm volatile("s_waitcnt lgkmcnt(" #n ")" ::: "memory")
; #define PG8_BAR __builtin_amdgcn_s_barrier()
; #define PG8_SCHED __builtin_amdgcn_sched_barrier(0)
;     __device__ __forceinline__ void operator()(f32x4 (&acc)[2][2][4][2], const Unit& u, int wr, int wc, int fr, int fq) const {
;         const bool isy = u.pn < 8; h16* dst = isy ? ybr : xpre; const int colb = (isy ? u.pn : u.pn - 8) * BM + wc * 32 + 8 * fq;
;         const int row0 = u.pm * BM + wr * 64 + fr;
; #pragma unroll
;         for (int ai = 0; ai < 2; ++ai)
; #pragma unroll
;             for (int m = 0; m < 4; ++m) { h16* rowp = dst + (size_t)(row0 + ai * HALF + m * 16) * DM + colb;
; #pragma unroll
;                 for (int bj = 0; bj < 2; ++bj) { f32x4 v0 = acc[ai][bj][m][0], v1 = acc[ai][bj][m][1];
;                     if (isy) {
; #pragma unroll
;                         for (int j = 0; j < 4; ++j) { v0[j] = gelu_tanh(v0[j]); v1[j] = gelu_tanh(v1[j]); } }
; template <class Epi>
; __device__ __forceinline__ void gemm_phase(LAS unsigned char* lds, const Gemm g0, const StaticOrder& S, const Epi& E) {
;     ...
;             PG8_BAR; PG8_WAIT_L(0); PG8_MMA(1, 0, At, B0); PG8_BAR; PG8_SCHED;
;             PG8_STAGE(PG8_SB(1, 1), b3 + hstep, voffB);
;             PG8_WAIT_V(6); PG8_BAR; PG8_MMA(1, 1, At, B1); PG8_BAR;
;         }
	s_waitcnt lgkmcnt(0)
	s_waitcnt lgkmcnt(0)
	v_mfma_f32_16x16x32_f16 v[62:65], v[142:145], v[178:181], v[62:65]
	v_mfma_f32_16x16x32_f16 v[58:61], v[156:159], v[178:181], v[58:61]
	v_mfma_f32_16x16x32_f16 v[46:49], v[142:145], v[186:189], v[46:49]
	v_mfma_f32_16x16x32_f16 v[42:45], v[156:159], v[186:189], v[42:45]
	v_mfma_f32_16x16x32_f16 v[30:33], v[142:145], v[194:197], v[30:33]
	v_mfma_f32_16x16x32_f16 v[26:29], v[156:159], v[194:197], v[26:29]
	v_mfma_f32_16x16x32_f16 v[14:17], v[142:145], v[202:205], v[14:17]
	v_mfma_f32_16x16x32_f16 v[10:13], v[156:159], v[202:205], v[10:13]
	v_mfma_f32_16x16x32_f16 v[62:65], v[152:155], v[182:185], v[62:65]
	v_mfma_f32_16x16x32_f16 v[58:61], v[174:177], v[182:185], v[58:61]
	v_mfma_f32_16x16x32_f16 v[46:49], v[152:155], v[190:193], v[46:49]
	v_mfma_f32_16x16x32_f16 v[42:45], v[174:177], v[190:193], v[42:45]
	v_mfma_f32_16x16x32_f16 v[30:33], v[152:155], v[198:201], v[30:33]
	v_mfma_f32_16x16x32_f16 v[26:29], v[174:177], v[198:201], v[26:29]
	v_mfma_f32_16x16x32_f16 v[14:17], v[152:155], v[206:209], v[14:17]
	v_mfma_f32_16x16x32_f16 v[10:13], v[174:177], v[206:209], v[10:13]
	s_barrier
	s_add_u32 s22, s34, 0x80080
	s_addc_u32 s23, s35, 0
	s_add_i32 s34, s61, s19
	s_mov_b32 m0, s34
	s_nop 0
	global_load_lds_dwordx4 v134, s[22:23]
	s_add_i32 m0, s34, 0x2000
	s_nop 0
	global_load_lds_dwordx4 v130, s[22:23]
	s_waitcnt vmcnt(6)
	s_barrier
	v_mfma_f32_16x16x32_f16 v[54:57], v[210:213], v[178:181], v[54:57]
	v_mfma_f32_16x16x32_f16 v[50:53], v[238:241], v[178:181], v[50:53]
	v_mfma_f32_16x16x32_f16 v[38:41], v[210:213], v[186:189], v[38:41]
	v_mfma_f32_16x16x32_f16 v[34:37], v[238:241], v[186:189], v[34:37]
	v_mfma_f32_16x16x32_f16 v[22:25], v[210:213], v[194:197], v[22:25]
	v_mfma_f32_16x16x32_f16 v[18:21], v[238:241], v[194:197], v[18:21]
	v_mfma_f32_16x16x32_f16 v[6:9], v[210:213], v[202:205], v[6:9]
	v_mfma_f32_16x16x32_f16 v[2:5], v[238:241], v[202:205], v[2:5]
	v_mfma_f32_16x16x32_f16 v[54:57], v[234:237], v[182:185], v[54:57]
	v_mfma_f32_16x16x32_f16 v[50:53], v[242:245], v[182:185], v[50:53]
	v_mfma_f32_16x16x32_f16 v[38:41], v[234:237], v[190:193], v[38:41]
	v_mfma_f32_16x16x32_f16 v[34:37], v[242:245], v[190:193], v[34:37]
	v_mfma_f32_16x16x32_f16 v[22:25], v[234:237], v[198:201], v[22:25]
	v_mfma_f32_16x16x32_f16 v[18:21], v[242:245], v[198:201], v[18:21]
	v_mfma_f32_16x16x32_f16 v[6:9], v[234:237], v[206:209], v[6:9]
	v_mfma_f32_16x16x32_f16 v[2:5], v[242:245], v[206:209], v[2:5]
	s_add_i32 s58, s58, 2
	s_add_u32 s25, s25, 0x100
	s_addc_u32 s53, s53, 0
	s_add_u32 s6, s6, 0x100
	s_addc_u32 s7, s7, 0
	s_cmp_gt_u32 s58, 29
	s_barrier
	s_cbranch_scc0 .LBB0_302
	s_cmp_lt_i32 s51, 8
	s_cselect_b64 s[34:35], -1, 0
	s_cmp_gt_i32 s51, 7
	s_cbranch_scc1 .LBB0_305
	v_mul_f32_e32 v143, 0x3d372713, v122
	v_mul_f32_e32 v143, v122, v143
	v_fma_f32 v143, v122, v143, v122
	v_mul_f32_e32 v143, 0xbfcc422a, v143
	v_mul_f32_e32 v143, 0x3fb8aa3b, v143
	v_exp_f32_e32 v143, v143
	v_mul_f32_e32 v142, 0x3d372713, v126
	v_mul_f32_e32 v142, v126, v142
	v_fma_f32 v142, v126, v142, v126
	v_add_f32_e32 v143, 1.0, v143
	v_rcp_f32_e32 v144, v143
	v_mul_f32_e32 v143, 0x3d372713, v127
	v_mul_f32_e32 v143, v127, v143
	v_fma_f32 v143, v127, v143, v127
	v_mul_f32_e32 v142, 0xbfcc422a, v142
	v_mul_f32_e32 v143, 0xbfcc422a, v143
	v_mul_f32_e32 v142, 0x3fb8aa3b, v142
	v_mul_f32_e32 v143, 0x3fb8aa3b, v143
	v_mul_f32_e32 v147, 0x3d372713, v124
	v_exp_f32_e32 v142, v142
	v_exp_f32_e32 v143, v143
	v_mul_f32_e32 v147, v124, v147
	v_fma_f32 v147, v124, v147, v124
	v_mul_f32_e32 v147, 0xbfcc422a, v147
	v_mul_f32_e32 v147, 0x3fb8aa3b, v147
	v_add_f32_e32 v142, 1.0, v142
	v_add_f32_e32 v143, 1.0, v143
	v_exp_f32_e32 v147, v147
	v_rcp_f32_e32 v142, v142
	v_rcp_f32_e32 v143, v143
	v_mul_f32_e32 v145, 0x3d372713, v123
	v_add_f32_e32 v147, 1.0, v147
	v_mul_f32_e32 v146, 0x3d372713, v128
	v_rcp_f32_e32 v152, v147
	v_mul_f32_e32 v147, 0x3d372713, v129
	v_pk_mul_f32 v[126:127], v[126:127], v[142:143]
	v_mul_f32_e32 v142, 0x3d372713, v125
	v_mul_f32_e32 v145, v123, v145
	v_mul_f32_e32 v146, v128, v146
	v_mul_f32_e32 v147, v129, v147
	v_mul_f32_e32 v142, v125, v142
	v_fma_f32 v145, v123, v145, v123
	v_fma_f32 v146, v128, v146, v128
	v_fma_f32 v147, v129, v147, v129
	v_fma_f32 v142, v125, v142, v125
	v_mul_f32_e32 v145, 0xbfcc422a, v145
	v_mul_f32_e32 v146, 0xbfcc422a, v146
	v_mul_f32_e32 v147, 0xbfcc422a, v147
	v_mul_f32_e32 v142, 0xbfcc422a, v142
	v_mul_f32_e32 v145, 0x3fb8aa3b, v145
	v_mul_f32_e32 v146, 0x3fb8aa3b, v146
	v_mul_f32_e32 v147, 0x3fb8aa3b, v147
	v_mul_f32_e32 v142, 0x3fb8aa3b, v142
	v_exp_f32_e32 v145, v145
	v_exp_f32_e32 v146, v146
	v_exp_f32_e32 v147, v147
	v_exp_f32_e32 v142, v142
	v_add_f32_e32 v145, 1.0, v145
	v_add_f32_e32 v146, 1.0, v146
	v_add_f32_e32 v147, 1.0, v147
	v_add_f32_e32 v142, 1.0, v142
	v_rcp_f32_e32 v145, v145
	v_rcp_f32_e32 v146, v146
	v_rcp_f32_e32 v147, v147
	v_rcp_f32_e32 v153, v142
	v_pk_mul_f32 v[122:123], v[122:123], v[144:145]
	v_pk_mul_f32 v[128:129], v[128:129], v[146:147]
	v_pk_mul_f32 v[124:125], v[124:125], v[152:153]

; #define PG8_STAGE(bufoff, gbase, voff) do { _Pragma("unroll") for (int _i = 0; _i < 2; ++_i) \
;         __builtin_amdgcn_global_load_lds((const unsigned*)((const char*)(gbase) + (voff)[_i]), (LAS unsigned*)(lds + (bufoff) + ldsw + _i * 8192), 16, 0, 0); } while (0)
; #define PG8_LDA(dst, b, h) do { _Pragma("unroll") for (int m = 0; m < 4; ++m) _Pragma("unroll") for (int k = 0; k < 2; ++k) dst[m][k] = *(const LAS f16x8*)(lds + PG8_SA(b, h) + aoff + m * 2048 + k * 1024); } while (0)
; #define PG8_LDB(dst, b, h) do { _Pragma("unroll") for (int n = 0; n < 2; ++n) _Pragma("unroll") for (int k = 0; k < 2; ++k) dst[n][k] = *(const LAS f16x8*)(lds + PG8_SB(b, h) + boff + n * 2048 + k * 1024); } while (0)
; #define PG8_MMA(ai, bj, At, Bt) do { __builtin_amdgcn_s_setprio(1); _Pragma("unroll") for (int m = 0; m < 4; ++m) _Pragma("unroll") for (int n = 0; n < 2; ++n) _Pragma("unroll") for (int k = 0; k < 2; ++k) \
;         acc[ai][bj][m][n] = __builtin_amdgcn_mfma_f32_16x16x32_f16(Bt[n][k], At[m][k], acc[ai][bj][m][n], 0, 0, 0); __builtin_amdgcn_s_setprio(0); } while (0)
; #define PG8_WAIT_V(n) asm volatile("s_waitcnt vmcnt(" #n ")" ::: "memory")
; #define PG8_WAIT_L(n) asm volatile("s_waitcnt lgkmcnt(" #n ")" ::: "memory")
; #define PG8_BAR __builtin_amdgcn_s_barrier()
; #define PG8_SCHED __builtin_amdgcn_sched_barrier(0)
; template <class Epi>
; __device__ __forceinline__ void gemm_phase(LAS unsigned char* lds, const Gemm g0, const StaticOrder& S, const Epi& E) {
;     ...
;             PG8_LDB(B0, 0, 0); PG8_SCHED; PG8_LDA(At, 0, 0); PG8_STAGE(PG8_SA(1, 1), a1 + hstep, voffA);
;             PG8_WAIT_L(8); PG8_BAR; PG8_WAIT_L(0); PG8_MMA(0, 0, At, B0); PG8_BAR; PG8_SCHED;
;             PG8_LDB(B1, 0, 1); PG8_STAGE(PG8_SB(0, 0), b2, voffB);
;             PG8_BAR; PG8_WAIT_L(0); PG8_MMA(0, 1, At, B1); PG8_BAR;
;             PG8_LDA(At, 0, 1); PG8_STAGE(PG8_SA(0, 0), a2, voffA);
;             PG8_BAR; PG8_WAIT_L(0); PG8_MMA(1, 0, At, B0); PG8_BAR; PG8_SCHED;
;             PG8_STAGE(PG8_SB(0, 1), b2 + hstep, voffB);
;             PG8_WAIT_V(6); PG8_BAR; PG8_MMA(1, 1, At, B1); PG8_BAR;
.LBB0_512:
	s_add_u32 s23, s12, 0xfff80080
	s_addc_u32 s48, s13, -1
	s_add_i32 s90, 0, 0x10000
	ds_read_b128 v[122:125], v165
	ds_read_b128 v[126:129], v165 offset:1024
	ds_read_b128 v[138:141], v165 offset:2048
	ds_read_b128 v[142:145], v165 offset:3072
	s_cmp_eq_u32 s22, 28
	s_cselect_b32 s51, s15, s48
	s_cselect_b32 s50, s24, s23
	s_cselect_b32 s49, s25, vcc_hi
	s_cselect_b32 s48, s53, vcc_lo
	s_add_i32 m0, s71, 0xc000
	ds_read_b128 v[146:149], v210
	ds_read_b128 v[150:153], v210 offset:1024
	ds_read_b128 v[154:157], v210 offset:2048
	ds_read_b128 v[158:161], v210 offset:3072
	ds_read_b128 v[188:191], v210 offset:4096
	ds_read_b128 v[192:195], v210 offset:5120
	ds_read_b128 v[196:199], v210 offset:6144
	global_load_lds_dwordx4 v186, s[12:13]
	s_add_i32 m0, s71, 0xe000
	ds_read_b128 v[200:203], v210 offset:7168
	global_load_lds_dwordx4 v184, s[12:13]
	s_waitcnt lgkmcnt(8)
	s_barrier
	s_waitcnt lgkmcnt(0)
	s_waitcnt lgkmcnt(0)
	v_mfma_f32_16x16x32_f16 v[134:137], v[122:125], v[146:149], v[134:137]
	v_mfma_f32_16x16x32_f16 v[130:133], v[138:141], v[146:149], v[130:133]
	v_mfma_f32_16x16x32_f16 v[110:113], v[122:125], v[154:157], v[110:113]
	v_mfma_f32_16x16x32_f16 v[106:109], v[138:141], v[154:157], v[106:109]
	v_mfma_f32_16x16x32_f16 v[94:97], v[122:125], v[188:191], v[94:97]
	v_mfma_f32_16x16x32_f16 v[90:93], v[138:141], v[188:191], v[90:93]
	v_mfma_f32_16x16x32_f16 v[78:81], v[122:125], v[196:199], v[78:81]
	v_mfma_f32_16x16x32_f16 v[74:77], v[138:141], v[196:199], v[74:77]
	v_mfma_f32_16x16x32_f16 v[134:137], v[126:129], v[150:153], v[134:137]
	v_mfma_f32_16x16x32_f16 v[130:133], v[142:145], v[150:153], v[130:133]
	v_mfma_f32_16x16x32_f16 v[110:113], v[126:129], v[158:161], v[110:113]
	v_mfma_f32_16x16x32_f16 v[106:109], v[142:145], v[158:161], v[106:109]
	v_mfma_f32_16x16x32_f16 v[94:97], v[126:129], v[192:195], v[94:97]
	v_mfma_f32_16x16x32_f16 v[90:93], v[142:145], v[192:195], v[90:93]
	v_mfma_f32_16x16x32_f16 v[78:81], v[126:129], v[200:203], v[78:81]
	v_mfma_f32_16x16x32_f16 v[74:77], v[142:145], v[200:203], v[74:77]
	s_barrier
	s_add_i32 s23, 0, 0x14000
	s_add_i32 s90, s90, s75
	ds_read_b128 v[212:215], v165 offset:16384
	ds_read_b128 v[234:237], v165 offset:17408
	ds_read_b128 v[238:241], v165 offset:18432
	v_add_u32_e32 v162, 0x80, v178
	s_mov_b32 m0, s90
	s_nop 0
	global_load_lds_dwordx4 v178, s[48:49]
	s_add_i32 m0, s90, 0x2000
	ds_read_b128 v[242:245], v165 offset:19456
	global_load_lds_dwordx4 v174, s[48:49]
	s_barrier
	s_waitcnt lgkmcnt(0)
	s_waitcnt lgkmcnt(0)
	v_mfma_f32_16x16x32_f16 v[118:121], v[212:215], v[146:149], v[118:121]
	v_mfma_f32_16x16x32_f16 v[114:117], v[238:241], v[146:149], v[114:117]
	v_mfma_f32_16x16x32_f16 v[102:105], v[212:215], v[154:157], v[102:105]
	v_mfma_f32_16x16x32_f16 v[98:101], v[238:241], v[154:157], v[98:101]
	v_mfma_f32_16x16x32_f16 v[86:89], v[212:215], v[188:191], v[86:89]
	v_mfma_f32_16x16x32_f16 v[82:85], v[238:241], v[188:191], v[82:85]
	v_mfma_f32_16x16x32_f16 v[70:73], v[212:215], v[196:199], v[70:73]
	v_mfma_f32_16x16x32_f16 v[66:69], v[238:241], v[196:199], v[66:69]
	v_mfma_f32_16x16x32_f16 v[118:121], v[234:237], v[150:153], v[118:121]
	v_mfma_f32_16x16x32_f16 v[114:117], v[242:245], v[150:153], v[114:117]
	v_mfma_f32_16x16x32_f16 v[102:105], v[234:237], v[158:161], v[102:105]
	v_mfma_f32_16x16x32_f16 v[98:101], v[242:245], v[158:161], v[98:101]
	v_mfma_f32_16x16x32_f16 v[86:89], v[234:237], v[192:195], v[86:89]
	v_mfma_f32_16x16x32_f16 v[82:85], v[242:245], v[192:195], v[82:85]
	v_mfma_f32_16x16x32_f16 v[70:73], v[234:237], v[200:203], v[70:73]
	v_mfma_f32_16x16x32_f16 v[66:69], v[242:245], v[200:203], v[66:69]
	s_mov_b32 m0, s71
	v_lshl_add_u64 v[170:171], s[50:51], 0, v[180:181]
	s_barrier
	ds_read_b128 v[146:149], v210 offset:16384
	ds_read_b128 v[150:153], v210 offset:17408
	ds_read_b128 v[154:157], v210 offset:18432
	ds_read_b128 v[158:161], v210 offset:19456
	ds_read_b128 v[188:191], v210 offset:20480
	ds_read_b128 v[192:195], v210 offset:21504
	ds_read_b128 v[196:199], v210 offset:22528
	ds_read_b128 v[200:203], v210 offset:23552
	global_load_lds_dwordx4 v[170:171], off
	v_lshl_add_u64 v[172:173], s[50:51], 0, v[176:177]
	s_mov_b32 m0, s61
	s_nop 0
	global_load_lds_dwordx4 v[172:173], off
	s_barrier
	s_waitcnt lgkmcnt(0)
	s_waitcnt lgkmcnt(0)
	v_mfma_f32_16x16x32_f16 v[62:65], v[122:125], v[146:149], v[62:65]
	v_mfma_f32_16x16x32_f16 v[58:61], v[138:141], v[146:149], v[58:61]
	v_mfma_f32_16x16x32_f16 v[46:49], v[122:125], v[154:157], v[46:49]
	v_mfma_f32_16x16x32_f16 v[42:45], v[138:141], v[154:157], v[42:45]
	v_mfma_f32_16x16x32_f16 v[30:33], v[122:125], v[188:191], v[30:33]
	v_mfma_f32_16x16x32_f16 v[26:29], v[138:141], v[188:191], v[26:29]
	v_mfma_f32_16x16x32_f16 v[14:17], v[122:125], v[196:199], v[14:17]
	v_mfma_f32_16x16x32_f16 v[10:13], v[138:141], v[196:199], v[10:13]
	v_mfma_f32_16x16x32_f16 v[62:65], v[126:129], v[150:153], v[62:65]
	v_mfma_f32_16x16x32_f16 v[58:61], v[142:145], v[150:153], v[58:61]
	v_mfma_f32_16x16x32_f16 v[46:49], v[126:129], v[158:161], v[46:49]
	v_mfma_f32_16x16x32_f16 v[42:45], v[142:145], v[158:161], v[42:45]
	v_mfma_f32_16x16x32_f16 v[30:33], v[126:129], v[192:195], v[30:33]
	v_mfma_f32_16x16x32_f16 v[26:29], v[142:145], v[192:195], v[26:29]
	v_mfma_f32_16x16x32_f16 v[14:17], v[126:129], v[200:203], v[14:17]
	v_mfma_f32_16x16x32_f16 v[10:13], v[142:145], v[200:203], v[10:13]
	s_barrier
	s_add_u32 s90, s48, 0x80000
	s_addc_u32 s91, s49, 0
	s_add_i32 s23, s23, s75
	s_mov_b32 m0, s23
	s_nop 0
	global_load_lds_dwordx4 v178, s[90:91]
	s_add_i32 m0, s23, 0x2000
	s_nop 0
	global_load_lds_dwordx4 v174, s[90:91]
	s_waitcnt vmcnt(6)
	s_barrier
; #define PG8_STAGE(bufoff, gbase, voff) do { _Pragma("unroll") for (int _i = 0; _i < 2; ++_i) \
;         __builtin_amdgcn_global_load_lds((const unsigned*)((const char*)(gbase) + (voff)[_i]), (LAS unsigned*)(lds + (bufoff) + ldsw + _i * 8192), 16, 0, 0); } while (0)
; #define PG8_LDA(dst, b, h) do { _Pragma("unroll") for (int m = 0; m < 4; ++m) _Pragma("unroll") for (int k = 0; k < 2; ++k) dst[m][k] = *(const LAS f16x8*)(lds + PG8_SA(b, h) + aoff + m * 2048 + k * 1024); } while (0)
; #define PG8_LDB(dst, b, h) do { _Pragma("unroll") for (int n = 0; n < 2; ++n) _Pragma("unroll") for (int k = 0; k < 2; ++k) dst[n][k] = *(const LAS f16x8*)(lds + PG8_SB(b, h) + boff + n * 2048 + k * 1024); } while (0)
; #define PG8_MMA(ai, bj, At, Bt) do { __builtin_amdgcn_s_setprio(1); _Pragma("unroll") for (int m = 0; m < 4; ++m) _Pragma("unroll") for (int n = 0; n < 2; ++n) _Pragma("unroll") for (int k = 0; k < 2; ++k) \
;         acc[ai][bj][m][n] = __builtin_amdgcn_mfma_f32_16x16x32_f16(Bt[n][k], At[m][k], acc[ai][bj][m][n], 0, 0, 0); __builtin_amdgcn_s_setprio(0); } while (0)
; #define PG8_WAIT_V(n) asm volatile("s_waitcnt vmcnt(" #n ")" ::: "memory")
; #define PG8_WAIT_L(n) asm volatile("s_waitcnt lgkmcnt(" #n ")" ::: "memory")
; #define PG8_BAR __builtin_amdgcn_s_barrier()
; #define PG8_SCHED __builtin_amdgcn_sched_barrier(0)
; template <class Epi>
; __device__ __forceinline__ void gemm_phase(LAS unsigned char* lds, const Gemm g0, const StaticOrder& S, const Epi& E) {
;     ...
;             PG8_WAIT_V(6); PG8_BAR; PG8_MMA(1, 1, At, B1); PG8_BAR;
;             PG8_LDB(B0, 1, 0); PG8_SCHED; PG8_LDA(At, 1, 0); PG8_STAGE(PG8_SA(0, 1), a2 + hstep, voffA);
;             PG8_WAIT_L(8); PG8_BAR; PG8_WAIT_L(0); PG8_MMA(0, 0, At, B0); PG8_BAR; PG8_SCHED;
;             PG8_LDB(B1, 1, 1); PG8_STAGE(PG8_SB(1, 0), b3, voffB);
;             PG8_BAR; PG8_WAIT_L(0); PG8_MMA(0, 1, At, B1); PG8_BAR;
	v_mfma_f32_16x16x32_f16 v[54:57], v[212:215], v[146:149], v[54:57]
	v_mfma_f32_16x16x32_f16 v[50:53], v[238:241], v[146:149], v[50:53]
	v_mfma_f32_16x16x32_f16 v[38:41], v[212:215], v[154:157], v[38:41]
	v_mfma_f32_16x16x32_f16 v[34:37], v[238:241], v[154:157], v[34:37]
	v_mfma_f32_16x16x32_f16 v[22:25], v[212:215], v[188:191], v[22:25]
	v_mfma_f32_16x16x32_f16 v[18:21], v[238:241], v[188:191], v[18:21]
	v_mfma_f32_16x16x32_f16 v[6:9], v[212:215], v[196:199], v[6:9]
	v_mfma_f32_16x16x32_f16 v[2:5], v[238:241], v[196:199], v[2:5]
	v_mfma_f32_16x16x32_f16 v[54:57], v[234:237], v[150:153], v[54:57]
	v_mfma_f32_16x16x32_f16 v[50:53], v[242:245], v[150:153], v[50:53]
	v_mfma_f32_16x16x32_f16 v[38:41], v[234:237], v[158:161], v[38:41]
	v_mfma_f32_16x16x32_f16 v[34:37], v[242:245], v[158:161], v[34:37]
	v_mfma_f32_16x16x32_f16 v[22:25], v[234:237], v[192:195], v[22:25]
	v_mfma_f32_16x16x32_f16 v[18:21], v[242:245], v[192:195], v[18:21]
	v_mfma_f32_16x16x32_f16 v[6:9], v[234:237], v[200:203], v[6:9]
	v_mfma_f32_16x16x32_f16 v[2:5], v[242:245], v[200:203], v[2:5]
	s_add_i32 s23, 0, 0x18000
	s_barrier
	ds_read_b128 v[122:125], v165 offset:32768
	ds_read_b128 v[126:129], v165 offset:33792
	ds_read_b128 v[138:141], v165 offset:34816
	ds_read_b128 v[142:145], v165 offset:35840
	s_add_u32 s50, s50, 0x80000
	s_addc_u32 s51, s51, 0
	s_mov_b32 m0, s74
	ds_read_b128 v[146:149], v210 offset:32768
	ds_read_b128 v[150:153], v210 offset:33792
	ds_read_b128 v[154:157], v210 offset:34816
	ds_read_b128 v[158:161], v210 offset:35840
	ds_read_b128 v[188:191], v210 offset:36864
	ds_read_b128 v[192:195], v210 offset:37888
	ds_read_b128 v[196:199], v210 offset:38912
	global_load_lds_dwordx4 v180, s[50:51]
	s_mov_b32 m0, s18
	ds_read_b128 v[200:203], v210 offset:39936
	global_load_lds_dwordx4 v176, s[50:51]
	s_waitcnt lgkmcnt(8)
	s_barrier
	s_waitcnt lgkmcnt(0)
	s_waitcnt lgkmcnt(0)
	v_mfma_f32_16x16x32_f16 v[134:137], v[122:125], v[146:149], v[134:137]
	v_mfma_f32_16x16x32_f16 v[130:133], v[138:141], v[146:149], v[130:133]
	v_mfma_f32_16x16x32_f16 v[110:113], v[122:125], v[154:157], v[110:113]
	v_mfma_f32_16x16x32_f16 v[106:109], v[138:141], v[154:157], v[106:109]
	v_mfma_f32_16x16x32_f16 v[94:97], v[122:125], v[188:191], v[94:97]
	v_mfma_f32_16x16x32_f16 v[90:93], v[138:141], v[188:191], v[90:93]
	v_mfma_f32_16x16x32_f16 v[78:81], v[122:125], v[196:199], v[78:81]
	v_mfma_f32_16x16x32_f16 v[74:77], v[138:141], v[196:199], v[74:77]
	v_mfma_f32_16x16x32_f16 v[134:137], v[126:129], v[150:153], v[134:137]
	v_mfma_f32_16x16x32_f16 v[130:133], v[142:145], v[150:153], v[130:133]
	v_mfma_f32_16x16x32_f16 v[110:113], v[126:129], v[158:161], v[110:113]
	v_mfma_f32_16x16x32_f16 v[106:109], v[142:145], v[158:161], v[106:109]
	v_mfma_f32_16x16x32_f16 v[94:97], v[126:129], v[192:195], v[94:97]
	v_mfma_f32_16x16x32_f16 v[90:93], v[142:145], v[192:195], v[90:93]
	v_mfma_f32_16x16x32_f16 v[78:81], v[126:129], v[200:203], v[78:81]
	v_mfma_f32_16x16x32_f16 v[74:77], v[142:145], v[200:203], v[74:77]
	s_barrier
	s_add_i32 s50, 0, 0x1c000
	s_add_i32 s23, s23, s75
	s_mov_b32 m0, s23
	ds_read_b128 v[212:215], v165 offset:49152
	ds_read_b128 v[234:237], v165 offset:50176
	ds_read_b128 v[238:241], v165 offset:51200
	global_load_lds_dwordx4 v162, s[48:49]
	s_add_i32 m0, s23, 0x2000
	ds_read_b128 v[242:245], v165 offset:52224
	global_load_lds_dwordx4 v164, s[48:49]
	s_barrier
	s_waitcnt lgkmcnt(0)
	s_waitcnt lgkmcnt(0)
	v_mfma_f32_16x16x32_f16 v[118:121], v[212:215], v[146:149], v[118:121]
	v_mfma_f32_16x16x32_f16 v[114:117], v[238:241], v[146:149], v[114:117]
	v_mfma_f32_16x16x32_f16 v[102:105], v[212:215], v[154:157], v[102:105]
	v_mfma_f32_16x16x32_f16 v[98:101], v[238:241], v[154:157], v[98:101]
	v_mfma_f32_16x16x32_f16 v[86:89], v[212:215], v[188:191], v[86:89]
	v_mfma_f32_16x16x32_f16 v[82:85], v[238:241], v[188:191], v[82:85]
	v_mfma_f32_16x16x32_f16 v[70:73], v[212:215], v[196:199], v[70:73]
	v_mfma_f32_16x16x32_f16 v[66:69], v[238:241], v[196:199], v[66:69]
	v_mfma_f32_16x16x32_f16 v[118:121], v[234:237], v[150:153], v[118:121]
	v_mfma_f32_16x16x32_f16 v[114:117], v[242:245], v[150:153], v[114:117]
	v_mfma_f32_16x16x32_f16 v[102:105], v[234:237], v[158:161], v[102:105]
	v_mfma_f32_16x16x32_f16 v[98:101], v[242:245], v[158:161], v[98:101]
	v_mfma_f32_16x16x32_f16 v[86:89], v[234:237], v[192:195], v[86:89]
	v_mfma_f32_16x16x32_f16 v[82:85], v[242:245], v[192:195], v[82:85]
	v_mfma_f32_16x16x32_f16 v[70:73], v[234:237], v[200:203], v[70:73]
	v_mfma_f32_16x16x32_f16 v[66:69], v[242:245], v[200:203], v[66:69]
	s_mov_b32 m0, s28
	v_lshl_add_u64 v[162:163], v[170:171], 0, s[64:65]
	s_barrier
; #define LAS __attribute__((address_space(3)))
; #define GAS __attribute__((address_space(1)))
; #define PG8_STAGE(bufoff, gbase, voff) do { _Pragma("unroll") for (int _i = 0; _i < 2; ++_i) \
;         __builtin_amdgcn_global_load_lds((const unsigned*)((const char*)(gbase) + (voff)[_i]), (LAS unsigned*)(lds + (bufoff) + ldsw + _i * 8192), 16, 0, 0); } while (0)
; #define PG8_LDA(dst, b, h) do { _Pragma("unroll") for (int m = 0; m < 4; ++m) _Pragma("unroll") for (int k = 0; k < 2; ++k) dst[m][k] = *(const LAS f16x8*)(lds + PG8_SA(b, h) + aoff + m * 2048 + k * 1024); } while (0)
; #define PG8_MMA(ai, bj, At, Bt) do { __builtin_amdgcn_s_setprio(1); _Pragma("unroll") for (int m = 0; m < 4; ++m) _Pragma("unroll") for (int n = 0; n < 2; ++n) _Pragma("unroll") for (int k = 0; k < 2; ++k) \
;         acc[ai][bj][m][n] = __builtin_amdgcn_mfma_f32_16x16x32_f16(Bt[n][k], At[m][k], acc[ai][bj][m][n], 0, 0, 0); __builtin_amdgcn_s_setprio(0); } while (0)
; #define PG8_WAIT_V(n) asm volatile("s_waitcnt vmcnt(" #n ")" ::: "memory")
; #define PG8_WAIT_L(n) asm volatile("s_waitcnt lgkmcnt(" #n ")" ::: "memory")
; #define PG8_BAR __builtin_amdgcn_s_barrier()
; #define PG8_SCHED __builtin_amdgcn_sched_barrier(0)
;     __device__ __forceinline__ void operator()(f32x4 (&acc)[2][2][4][2], const Unit& u, int wr, int wc, int fr, int fq) const {
;         const int row0 = u.pm * BM + wr * 64 + fr, colb = u.pn * BM + wc * 32 + 8 * fq;
;         const bool hasln = pstats != nullptr, haszh = zh != nullptr;
;         LAS float* slot = vl + (wr * 4 + wc) * 256;
;         f32x4 rn[2][2]; float ssm[8], ssq[8]; f32x2 stn = {0.f, 0.f};
;         { const int lane = fr + 16 * fq, cL = u.pn * BM + wc * 32 + (lane < 32 ? lane : 96 + lane);
;           float vg = 0.f, vb = 0.f, vt = 0.f;
;           if (hasln) { vg = *(const GAS float*)(pg + cL); vb = *(const GAS float*)(pb + cL); }
;           if (haszh) vt = *(const GAS float*)(tg + cL);
; template <class Epi>
; __device__ __forceinline__ void gemm_phase(LAS unsigned char* lds, const Gemm g0, const StaticOrder& S, const Epi& E) {
;     ...
;             PG8_LDA(At, 1, 1); PG8_STAGE(PG8_SA(1, 0), a3, voffA);
;             PG8_BAR; PG8_WAIT_L(0); PG8_MMA(1, 0, At, B0); PG8_BAR; PG8_SCHED;
;             PG8_STAGE(PG8_SB(1, 1), b3 + hstep, voffB);
;             PG8_WAIT_V(6); PG8_BAR; PG8_MMA(1, 1, At, B1); PG8_BAR;
;         }
	ds_read_b128 v[146:149], v210 offset:49152
	ds_read_b128 v[150:153], v210 offset:50176
	ds_read_b128 v[154:157], v210 offset:51200
	ds_read_b128 v[158:161], v210 offset:52224
	ds_read_b128 v[188:191], v210 offset:53248
	ds_read_b128 v[192:195], v210 offset:54272
	ds_read_b128 v[196:199], v210 offset:55296
	ds_read_b128 v[200:203], v210 offset:56320
	global_load_lds_dwordx4 v[162:163], off
	v_lshl_add_u64 v[162:163], v[172:173], 0, s[64:65]
	s_mov_b32 m0, s29
	s_nop 0
	global_load_lds_dwordx4 v[162:163], off
	s_barrier
	s_waitcnt lgkmcnt(0)
	s_waitcnt lgkmcnt(0)
	v_mfma_f32_16x16x32_f16 v[62:65], v[122:125], v[146:149], v[62:65]
	v_mfma_f32_16x16x32_f16 v[58:61], v[138:141], v[146:149], v[58:61]
	v_mfma_f32_16x16x32_f16 v[46:49], v[122:125], v[154:157], v[46:49]
	v_mfma_f32_16x16x32_f16 v[42:45], v[138:141], v[154:157], v[42:45]
	v_mfma_f32_16x16x32_f16 v[30:33], v[122:125], v[188:191], v[30:33]
	v_mfma_f32_16x16x32_f16 v[26:29], v[138:141], v[188:191], v[26:29]
	v_mfma_f32_16x16x32_f16 v[14:17], v[122:125], v[196:199], v[14:17]
	v_mfma_f32_16x16x32_f16 v[10:13], v[138:141], v[196:199], v[10:13]
	v_mfma_f32_16x16x32_f16 v[62:65], v[126:129], v[150:153], v[62:65]
	v_mfma_f32_16x16x32_f16 v[58:61], v[142:145], v[150:153], v[58:61]
	v_mfma_f32_16x16x32_f16 v[46:49], v[126:129], v[158:161], v[46:49]
	v_mfma_f32_16x16x32_f16 v[42:45], v[142:145], v[158:161], v[42:45]
	v_mfma_f32_16x16x32_f16 v[30:33], v[126:129], v[192:195], v[30:33]
	v_mfma_f32_16x16x32_f16 v[26:29], v[142:145], v[192:195], v[26:29]
	v_mfma_f32_16x16x32_f16 v[14:17], v[126:129], v[200:203], v[14:17]
	v_mfma_f32_16x16x32_f16 v[10:13], v[142:145], v[200:203], v[10:13]
	s_barrier
	s_add_u32 s48, s48, 0x80080
	s_addc_u32 s49, s49, 0
	s_add_i32 s23, s50, s75
	s_mov_b32 m0, s23
	s_nop 0
	global_load_lds_dwordx4 v178, s[48:49]
	s_add_i32 m0, s23, 0x2000
	s_nop 0
	global_load_lds_dwordx4 v174, s[48:49]
	s_waitcnt vmcnt(6)
	s_barrier
	v_mfma_f32_16x16x32_f16 v[54:57], v[212:215], v[146:149], v[54:57]
	v_mfma_f32_16x16x32_f16 v[50:53], v[238:241], v[146:149], v[50:53]
	v_mfma_f32_16x16x32_f16 v[38:41], v[212:215], v[154:157], v[38:41]
	v_mfma_f32_16x16x32_f16 v[34:37], v[238:241], v[154:157], v[34:37]
	v_mfma_f32_16x16x32_f16 v[22:25], v[212:215], v[188:191], v[22:25]
	v_mfma_f32_16x16x32_f16 v[18:21], v[238:241], v[188:191], v[18:21]
	v_mfma_f32_16x16x32_f16 v[6:9], v[212:215], v[196:199], v[6:9]
	v_mfma_f32_16x16x32_f16 v[2:5], v[238:241], v[196:199], v[2:5]
	v_mfma_f32_16x16x32_f16 v[54:57], v[234:237], v[150:153], v[54:57]
	v_mfma_f32_16x16x32_f16 v[50:53], v[242:245], v[150:153], v[50:53]
	v_mfma_f32_16x16x32_f16 v[38:41], v[234:237], v[158:161], v[38:41]
	v_mfma_f32_16x16x32_f16 v[34:37], v[242:245], v[158:161], v[34:37]
	v_mfma_f32_16x16x32_f16 v[22:25], v[234:237], v[192:195], v[22:25]
	v_mfma_f32_16x16x32_f16 v[18:21], v[242:245], v[192:195], v[18:21]
	v_mfma_f32_16x16x32_f16 v[6:9], v[234:237], v[200:203], v[6:9]
	v_mfma_f32_16x16x32_f16 v[2:5], v[242:245], v[200:203], v[2:5]
	s_add_i32 s22, s22, 2
	s_add_u32 vcc_lo, vcc_lo, 0x100
	s_addc_u32 vcc_hi, vcc_hi, 0
	s_add_u32 s12, s12, 0x100
	s_addc_u32 s13, s13, 0
	s_cmp_gt_u32 s22, 29
	s_barrier
	s_cbranch_scc0 .LBB0_512
	s_lshl_b32 s12, s83, 8
	s_or_b32 s15, s12, s31
	v_add_u32_e32 v122, s15, v206
	v_cndmask_b32_e64 v124, 0, 1, s[44:45]
	v_ashrrev_i32_e32 v123, 31, v122
	v_mov_b32_e32 v196, 0
	v_cmp_ne_u32_e64 s[12:13], 1, v124
	s_andn2_b64 vcc, exec, s[44:45]
	v_mov_b32_e32 v124, 0
	v_mov_b32_e32 v125, 0
	s_cbranch_vccnz .LBB0_515
	v_lshlrev_b64 v[124:125], 2, v[122:123]
	v_lshl_add_u64 v[126:127], s[80:81], 0, v[124:125]
	v_lshl_add_u64 v[124:125], s[58:59], 0, v[124:125]
	global_load_dword v125, v[124:125], off
	s_nop 0
	global_load_dword v124, v[126:127], off

; #define PG8_STAGE(bufoff, gbase, voff) do { _Pragma("unroll") for (int _i = 0; _i < 2; ++_i) \
;         __builtin_amdgcn_global_load_lds((const unsigned*)((const char*)(gbase) + (voff)[_i]), (LAS unsigned*)(lds + (bufoff) + ldsw + _i * 8192), 16, 0, 0); } while (0)
; #define PG8_LDA(dst, b, h) do { _Pragma("unroll") for (int m = 0; m < 4; ++m) _Pragma("unroll") for (int k = 0; k < 2; ++k) dst[m][k] = *(const LAS f16x8*)(lds + PG8_SA(b, h) + aoff + m * 2048 + k * 1024); } while (0)
; #define PG8_LDB(dst, b, h) do { _Pragma("unroll") for (int n = 0; n < 2; ++n) _Pragma("unroll") for (int k = 0; k < 2; ++k) dst[n][k] = *(const LAS f16x8*)(lds + PG8_SB(b, h) + boff + n * 2048 + k * 1024); } while (0)
; #define PG8_MMA(ai, bj, At, Bt) do { __builtin_amdgcn_s_setprio(1); _Pragma("unroll") for (int m = 0; m < 4; ++m) _Pragma("unroll") for (int n = 0; n < 2; ++n) _Pragma("unroll") for (int k = 0; k < 2; ++k) \
;         acc[ai][bj][m][n] = __builtin_amdgcn_mfma_f32_16x16x32_f16(Bt[n][k], At[m][k], acc[ai][bj][m][n], 0, 0, 0); __builtin_amdgcn_s_setprio(0); } while (0)
; #define PG8_WAIT_V(n) asm volatile("s_waitcnt vmcnt(" #n ")" ::: "memory")
; #define PG8_WAIT_L(n) asm volatile("s_waitcnt lgkmcnt(" #n ")" ::: "memory")
; #define PG8_BAR __builtin_amdgcn_s_barrier()
; #define PG8_SCHED __builtin_amdgcn_sched_barrier(0)
; template <class Epi>
; __device__ __forceinline__ void gemm_phase(LAS unsigned char* lds, const Gemm g0, const StaticOrder& S, const Epi& E) {
;     ...
;             PG8_LDB(B0, 0, 0); PG8_SCHED; PG8_LDA(At, 0, 0); PG8_STAGE(PG8_SA(1, 1), a1 + hstep, voffA);
;             PG8_WAIT_L(8); PG8_BAR; PG8_WAIT_L(0); PG8_MMA(0, 0, At, B0); PG8_BAR; PG8_SCHED;
;             PG8_LDB(B1, 0, 1); PG8_STAGE(PG8_SB(0, 0), b2, voffB);
;             PG8_BAR; PG8_WAIT_L(0); PG8_MMA(0, 1, At, B1); PG8_BAR;
;             PG8_LDA(At, 0, 1); PG8_STAGE(PG8_SA(0, 0), a2, voffA);
;             PG8_BAR; PG8_WAIT_L(0); PG8_MMA(1, 0, At, B0); PG8_BAR; PG8_SCHED;
;             PG8_STAGE(PG8_SB(0, 1), b2 + hstep, voffB);
;             PG8_WAIT_V(6); PG8_BAR; PG8_MMA(1, 1, At, B1); PG8_BAR;
.LBB0_620:
	s_add_u32 s58, s50, 0xfff80080
	s_addc_u32 s59, s51, -1
	s_and_b64 s[22:23], s[52:53], exec
	s_cselect_b32 s59, s37, s59
	s_cselect_b32 s58, s74, s58
	s_add_i32 s82, 0, 0x10000
	ds_read_b128 v[60:63], v187
	ds_read_b128 v[64:67], v187 offset:1024
	ds_read_b128 v[78:81], v187 offset:2048
	ds_read_b128 v[82:85], v187 offset:3072
	s_and_b64 s[22:23], s[52:53], exec
	s_cselect_b32 s53, s35, s25
	s_cselect_b32 s52, s75, s24
	s_add_i32 m0, s18, 0xc000
	ds_read_b128 v[86:89], v213
	ds_read_b128 v[90:93], v213 offset:1024
	ds_read_b128 v[194:197], v213 offset:2048
	ds_read_b128 v[234:237], v213 offset:3072
	ds_read_b128 v[238:241], v213 offset:4096
	ds_read_b128 v[242:245], v213 offset:5120
	ds_read_b128 v[246:249], v213 offset:6144
	global_load_lds_dwordx4 v184, s[50:51]
	s_add_i32 m0, s18, 0xe000
	ds_read_b128 v[226:229], v213 offset:7168
	global_load_lds_dwordx4 v182, s[50:51]
	s_waitcnt lgkmcnt(8)
	s_barrier
	s_waitcnt lgkmcnt(0)
	s_waitcnt lgkmcnt(0)
	v_mfma_f32_16x16x32_f16 v[158:161], v[60:63], v[86:89], v[158:161]
	v_mfma_f32_16x16x32_f16 v[150:153], v[78:81], v[86:89], v[150:153]
	v_mfma_f32_16x16x32_f16 v[142:145], v[60:63], v[194:197], v[142:145]
	v_mfma_f32_16x16x32_f16 v[134:137], v[78:81], v[194:197], v[134:137]
	v_mfma_f32_16x16x32_f16 v[126:129], v[60:63], v[238:241], v[126:129]
	v_mfma_f32_16x16x32_f16 v[118:121], v[78:81], v[238:241], v[118:121]
	v_mfma_f32_16x16x32_f16 v[110:113], v[60:63], v[246:249], v[110:113]
	v_mfma_f32_16x16x32_f16 v[102:105], v[78:81], v[246:249], v[102:105]
	v_mfma_f32_16x16x32_f16 v[158:161], v[64:67], v[90:93], v[158:161]
	v_mfma_f32_16x16x32_f16 v[150:153], v[82:85], v[90:93], v[150:153]
	v_mfma_f32_16x16x32_f16 v[142:145], v[64:67], v[234:237], v[142:145]
	v_mfma_f32_16x16x32_f16 v[134:137], v[82:85], v[234:237], v[134:137]
	v_mfma_f32_16x16x32_f16 v[126:129], v[64:67], v[242:245], v[126:129]
	v_mfma_f32_16x16x32_f16 v[118:121], v[82:85], v[242:245], v[118:121]
	v_mfma_f32_16x16x32_f16 v[110:113], v[64:67], v[226:229], v[110:113]
	v_mfma_f32_16x16x32_f16 v[102:105], v[82:85], v[226:229], v[102:105]
	s_barrier
	s_add_i32 s83, 0, 0x14000
	s_add_i32 s22, s82, s5
	s_mov_b32 m0, s22
	ds_read_b128 v[162:165], v187 offset:16384
	ds_read_b128 v[222:225], v187 offset:17408
	ds_read_b128 v[214:217], v187 offset:18432
	global_load_lds_dwordx4 v178, s[52:53]
	s_add_i32 m0, s22, 0x2000
	ds_read_b128 v[170:173], v187 offset:19456
	global_load_lds_dwordx4 v174, s[52:53]
	s_barrier
	s_waitcnt lgkmcnt(0)
	s_waitcnt lgkmcnt(0)
	v_mfma_f32_16x16x32_f16 v[154:157], v[162:165], v[86:89], v[154:157]
	v_mfma_f32_16x16x32_f16 v[86:89], v[214:217], v[86:89], v[146:149]
	v_mfma_f32_16x16x32_f16 v[130:133], v[214:217], v[194:197], v[130:133]
	v_mfma_f32_16x16x32_f16 v[122:125], v[162:165], v[238:241], v[122:125]
	v_mfma_f32_16x16x32_f16 v[114:117], v[214:217], v[238:241], v[114:117]
	v_mfma_f32_16x16x32_f16 v[106:109], v[162:165], v[246:249], v[106:109]
	v_mfma_f32_16x16x32_f16 v[98:101], v[214:217], v[246:249], v[98:101]
	v_mfma_f32_16x16x32_f16 v[154:157], v[222:225], v[90:93], v[154:157]
	v_mfma_f32_16x16x32_f16 v[86:89], v[170:173], v[90:93], v[86:89]
	v_mfma_f32_16x16x32_f16 v[90:93], v[162:165], v[194:197], v[138:141]
	v_mfma_f32_16x16x32_f16 v[130:133], v[170:173], v[234:237], v[130:133]
	v_mfma_f32_16x16x32_f16 v[122:125], v[222:225], v[242:245], v[122:125]
	v_mfma_f32_16x16x32_f16 v[114:117], v[170:173], v[242:245], v[114:117]
	v_mfma_f32_16x16x32_f16 v[106:109], v[222:225], v[226:229], v[106:109]
	v_mfma_f32_16x16x32_f16 v[98:101], v[170:173], v[226:229], v[98:101]
	v_mfma_f32_16x16x32_f16 v[90:93], v[222:225], v[234:237], v[90:93]
	s_mov_b32 m0, s18
	s_barrier
	ds_read_b128 v[138:141], v213 offset:16384
	ds_read_b128 v[146:149], v213 offset:17408
	ds_read_b128 v[194:197], v213 offset:18432
	ds_read_b128 v[226:229], v213 offset:19456
	ds_read_b128 v[234:237], v213 offset:20480
	ds_read_b128 v[238:241], v213 offset:21504
	ds_read_b128 v[242:245], v213 offset:22528
	global_load_lds_dwordx4 v180, s[58:59]
	s_mov_b32 m0, s19
	ds_read_b128 v[246:249], v213 offset:23552
	global_load_lds_dwordx4 v176, s[58:59]
	s_barrier
	s_waitcnt lgkmcnt(0)
	s_waitcnt lgkmcnt(0)
	v_mfma_f32_16x16x32_f16 v[94:97], v[60:63], v[138:141], v[94:97]
	v_mfma_f32_16x16x32_f16 v[68:71], v[78:81], v[138:141], v[70:73]
	v_mfma_f32_16x16x32_f16 v[46:49], v[60:63], v[194:197], v[46:49]
	v_mfma_f32_16x16x32_f16 v[38:41], v[78:81], v[194:197], v[38:41]
	v_mfma_f32_16x16x32_f16 v[30:33], v[60:63], v[234:237], v[30:33]
	v_mfma_f32_16x16x32_f16 v[22:25], v[78:81], v[234:237], v[22:25]
	v_mfma_f32_16x16x32_f16 v[14:17], v[60:63], v[242:245], v[14:17]
	v_mfma_f32_16x16x32_f16 v[6:9], v[78:81], v[242:245], v[6:9]
	v_mfma_f32_16x16x32_f16 v[94:97], v[64:67], v[146:149], v[94:97]
	v_mfma_f32_16x16x32_f16 v[68:71], v[82:85], v[146:149], v[68:71]
	v_mfma_f32_16x16x32_f16 v[46:49], v[64:67], v[226:229], v[46:49]
	v_mfma_f32_16x16x32_f16 v[38:41], v[82:85], v[226:229], v[38:41]
	v_mfma_f32_16x16x32_f16 v[30:33], v[64:67], v[238:241], v[30:33]
	v_mfma_f32_16x16x32_f16 v[22:25], v[82:85], v[238:241], v[22:25]
	v_mfma_f32_16x16x32_f16 v[14:17], v[64:67], v[246:249], v[14:17]
	v_mfma_f32_16x16x32_f16 v[6:9], v[82:85], v[246:249], v[6:9]
	s_barrier
	s_add_u32 s22, s52, 0x80000
	s_addc_u32 s23, s53, 0
	s_add_i32 s82, s83, s5
	s_mov_b32 m0, s82
	s_nop 0
	global_load_lds_dwordx4 v178, s[22:23]
	s_add_i32 m0, s82, 0x2000
	s_nop 0
	global_load_lds_dwordx4 v174, s[22:23]
	s_waitcnt vmcnt(6)
	s_barrier
; #define PG8_STAGE(bufoff, gbase, voff) do { _Pragma("unroll") for (int _i = 0; _i < 2; ++_i) \
;         __builtin_amdgcn_global_load_lds((const unsigned*)((const char*)(gbase) + (voff)[_i]), (LAS unsigned*)(lds + (bufoff) + ldsw + _i * 8192), 16, 0, 0); } while (0)
; #define PG8_LDA(dst, b, h) do { _Pragma("unroll") for (int m = 0; m < 4; ++m) _Pragma("unroll") for (int k = 0; k < 2; ++k) dst[m][k] = *(const LAS f16x8*)(lds + PG8_SA(b, h) + aoff + m * 2048 + k * 1024); } while (0)
; #define PG8_LDB(dst, b, h) do { _Pragma("unroll") for (int n = 0; n < 2; ++n) _Pragma("unroll") for (int k = 0; k < 2; ++k) dst[n][k] = *(const LAS f16x8*)(lds + PG8_SB(b, h) + boff + n * 2048 + k * 1024); } while (0)
; #define PG8_MMA(ai, bj, At, Bt) do { __builtin_amdgcn_s_setprio(1); _Pragma("unroll") for (int m = 0; m < 4; ++m) _Pragma("unroll") for (int n = 0; n < 2; ++n) _Pragma("unroll") for (int k = 0; k < 2; ++k) \
;         acc[ai][bj][m][n] = __builtin_amdgcn_mfma_f32_16x16x32_f16(Bt[n][k], At[m][k], acc[ai][bj][m][n], 0, 0, 0); __builtin_amdgcn_s_setprio(0); } while (0)
; #define PG8_WAIT_V(n) asm volatile("s_waitcnt vmcnt(" #n ")" ::: "memory")
; #define PG8_WAIT_L(n) asm volatile("s_waitcnt lgkmcnt(" #n ")" ::: "memory")
; #define PG8_BAR __builtin_amdgcn_s_barrier()
; #define PG8_SCHED __builtin_amdgcn_sched_barrier(0)
; template <class Epi>
; __device__ __forceinline__ void gemm_phase(LAS unsigned char* lds, const Gemm g0, const StaticOrder& S, const Epi& E) {
;     ...
;             PG8_WAIT_V(6); PG8_BAR; PG8_MMA(1, 1, At, B1); PG8_BAR;
;             PG8_LDB(B0, 1, 0); PG8_SCHED; PG8_LDA(At, 1, 0); PG8_STAGE(PG8_SA(0, 1), a2 + hstep, voffA);
;             PG8_WAIT_L(8); PG8_BAR; PG8_WAIT_L(0); PG8_MMA(0, 0, At, B0); PG8_BAR; PG8_SCHED;
;             PG8_LDB(B1, 1, 1); PG8_STAGE(PG8_SB(1, 0), b3, voffB);
;             PG8_BAR; PG8_WAIT_L(0); PG8_MMA(0, 1, At, B1); PG8_BAR;
	v_mfma_f32_16x16x32_f16 v[50:53], v[214:217], v[138:141], v[50:53]
	v_mfma_f32_16x16x32_f16 v[42:45], v[162:165], v[194:197], v[42:45]
	v_mfma_f32_16x16x32_f16 v[34:37], v[214:217], v[194:197], v[34:37]
	v_mfma_f32_16x16x32_f16 v[26:29], v[162:165], v[234:237], v[26:29]
	v_mfma_f32_16x16x32_f16 v[18:21], v[214:217], v[234:237], v[18:21]
	v_mfma_f32_16x16x32_f16 v[10:13], v[162:165], v[242:245], v[10:13]
	v_mfma_f32_16x16x32_f16 v[2:5], v[214:217], v[242:245], v[2:5]
	v_mfma_f32_16x16x32_f16 v[60:63], v[162:165], v[138:141], v[74:77]
	v_mfma_f32_16x16x32_f16 v[50:53], v[170:173], v[146:149], v[50:53]
	v_mfma_f32_16x16x32_f16 v[42:45], v[222:225], v[226:229], v[42:45]
	v_mfma_f32_16x16x32_f16 v[34:37], v[170:173], v[226:229], v[34:37]
	v_mfma_f32_16x16x32_f16 v[26:29], v[222:225], v[238:241], v[26:29]
	v_mfma_f32_16x16x32_f16 v[18:21], v[170:173], v[238:241], v[18:21]
	v_mfma_f32_16x16x32_f16 v[10:13], v[222:225], v[246:249], v[10:13]
	v_mfma_f32_16x16x32_f16 v[2:5], v[170:173], v[246:249], v[2:5]
	v_mfma_f32_16x16x32_f16 v[60:63], v[222:225], v[146:149], v[60:63]
	s_add_i32 s82, 0, 0x18000
	s_barrier
	ds_read_b128 v[64:67], v187 offset:32768
	ds_read_b128 v[74:77], v187 offset:33792
	ds_read_b128 v[78:81], v187 offset:34816
	ds_read_b128 v[82:85], v187 offset:35840
	s_add_u32 s22, s58, 0x80000
	s_addc_u32 s23, s59, 0
	s_mov_b32 m0, s28
	ds_read_b128 v[138:141], v213 offset:32768
	ds_read_b128 v[146:149], v213 offset:33792
	ds_read_b128 v[162:165], v213 offset:34816
	ds_read_b128 v[170:173], v213 offset:35840
	ds_read_b128 v[194:197], v213 offset:36864
	ds_read_b128 v[214:217], v213 offset:37888
	ds_read_b128 v[222:225], v213 offset:38912
	global_load_lds_dwordx4 v180, s[22:23]
	s_mov_b32 m0, s29
	ds_read_b128 v[226:229], v213 offset:39936
	global_load_lds_dwordx4 v176, s[22:23]
	s_waitcnt lgkmcnt(8)
	s_barrier
	s_waitcnt lgkmcnt(0)
	s_waitcnt lgkmcnt(0)
	v_mfma_f32_16x16x32_f16 v[158:161], v[64:67], v[138:141], v[158:161]
	v_mfma_f32_16x16x32_f16 v[150:153], v[78:81], v[138:141], v[150:153]
	v_mfma_f32_16x16x32_f16 v[142:145], v[64:67], v[162:165], v[142:145]
	v_mfma_f32_16x16x32_f16 v[134:137], v[78:81], v[162:165], v[134:137]
	v_mfma_f32_16x16x32_f16 v[126:129], v[64:67], v[194:197], v[126:129]
	v_mfma_f32_16x16x32_f16 v[118:121], v[78:81], v[194:197], v[118:121]
	v_mfma_f32_16x16x32_f16 v[110:113], v[64:67], v[222:225], v[110:113]
	v_mfma_f32_16x16x32_f16 v[102:105], v[78:81], v[222:225], v[102:105]
	v_mfma_f32_16x16x32_f16 v[158:161], v[74:77], v[146:149], v[158:161]
	v_mfma_f32_16x16x32_f16 v[150:153], v[82:85], v[146:149], v[150:153]
	v_mfma_f32_16x16x32_f16 v[142:145], v[74:77], v[170:173], v[142:145]
	v_mfma_f32_16x16x32_f16 v[134:137], v[82:85], v[170:173], v[134:137]
	v_mfma_f32_16x16x32_f16 v[126:129], v[74:77], v[214:217], v[126:129]
	v_mfma_f32_16x16x32_f16 v[118:121], v[82:85], v[214:217], v[118:121]
	v_mfma_f32_16x16x32_f16 v[110:113], v[74:77], v[226:229], v[110:113]
	v_mfma_f32_16x16x32_f16 v[102:105], v[82:85], v[226:229], v[102:105]
	s_barrier
	s_add_i32 s83, 0, 0x1c000
	s_add_i32 s22, s82, s5
	ds_read_b128 v[234:237], v187 offset:49152
	ds_read_b128 v[238:241], v187 offset:50176
	ds_read_b128 v[242:245], v187 offset:51200
	s_mov_b32 m0, s22
	s_nop 0
	global_load_lds_dwordx4 v186, s[52:53]
	s_add_i32 m0, s22, 0x2000
	ds_read_b128 v[246:249], v187 offset:52224
	global_load_lds_dwordx4 v190, s[52:53]
	s_barrier
; #define PG8_STAGE(bufoff, gbase, voff) do { _Pragma("unroll") for (int _i = 0; _i < 2; ++_i) \
;         __builtin_amdgcn_global_load_lds((const unsigned*)((const char*)(gbase) + (voff)[_i]), (LAS unsigned*)(lds + (bufoff) + ldsw + _i * 8192), 16, 0, 0); } while (0)
; #define PG8_LDA(dst, b, h) do { _Pragma("unroll") for (int m = 0; m < 4; ++m) _Pragma("unroll") for (int k = 0; k < 2; ++k) dst[m][k] = *(const LAS f16x8*)(lds + PG8_SA(b, h) + aoff + m * 2048 + k * 1024); } while (0)
; #define PG8_MMA(ai, bj, At, Bt) do { __builtin_amdgcn_s_setprio(1); _Pragma("unroll") for (int m = 0; m < 4; ++m) _Pragma("unroll") for (int n = 0; n < 2; ++n) _Pragma("unroll") for (int k = 0; k < 2; ++k) \
;         acc[ai][bj][m][n] = __builtin_amdgcn_mfma_f32_16x16x32_f16(Bt[n][k], At[m][k], acc[ai][bj][m][n], 0, 0, 0); __builtin_amdgcn_s_setprio(0); } while (0)
; #define PG8_WAIT_V(n) asm volatile("s_waitcnt vmcnt(" #n ")" ::: "memory")
; #define PG8_WAIT_L(n) asm volatile("s_waitcnt lgkmcnt(" #n ")" ::: "memory")
; #define PG8_BAR __builtin_amdgcn_s_barrier()
; #define PG8_SCHED __builtin_amdgcn_sched_barrier(0)
; template <class Epi>
; __device__ __forceinline__ void gemm_phase(LAS unsigned char* lds, const Gemm g0, const StaticOrder& S, const Epi& E) {
;     ...
;             PG8_BAR; PG8_WAIT_L(0); PG8_MMA(0, 1, At, B1); PG8_BAR;
;             PG8_LDA(At, 1, 1); PG8_STAGE(PG8_SA(1, 0), a3, voffA);
;             PG8_BAR; PG8_WAIT_L(0); PG8_MMA(1, 0, At, B0); PG8_BAR; PG8_SCHED;
;             PG8_STAGE(PG8_SB(1, 1), b3 + hstep, voffB);
;             PG8_WAIT_V(6); PG8_BAR; PG8_MMA(1, 1, At, B1); PG8_BAR;
;         }
	s_waitcnt lgkmcnt(0)
	s_waitcnt lgkmcnt(0)
	v_mfma_f32_16x16x32_f16 v[154:157], v[234:237], v[138:141], v[154:157]
	v_mfma_f32_16x16x32_f16 v[86:89], v[242:245], v[138:141], v[86:89]
	v_mfma_f32_16x16x32_f16 v[154:157], v[238:241], v[146:149], v[154:157]
	v_mfma_f32_16x16x32_f16 v[146:149], v[246:249], v[146:149], v[86:89]
	v_mfma_f32_16x16x32_f16 v[86:89], v[234:237], v[162:165], v[90:93]
	v_mfma_f32_16x16x32_f16 v[138:141], v[238:241], v[170:173], v[86:89]
	v_mfma_f32_16x16x32_f16 v[86:89], v[242:245], v[162:165], v[130:133]
	v_mfma_f32_16x16x32_f16 v[130:133], v[246:249], v[170:173], v[86:89]
	v_mfma_f32_16x16x32_f16 v[86:89], v[234:237], v[194:197], v[122:125]
	v_mfma_f32_16x16x32_f16 v[122:125], v[238:241], v[214:217], v[86:89]
	v_mfma_f32_16x16x32_f16 v[86:89], v[242:245], v[194:197], v[114:117]
	v_mfma_f32_16x16x32_f16 v[114:117], v[246:249], v[214:217], v[86:89]
	v_mfma_f32_16x16x32_f16 v[86:89], v[234:237], v[222:225], v[106:109]
	v_mfma_f32_16x16x32_f16 v[106:109], v[238:241], v[226:229], v[86:89]
	v_mfma_f32_16x16x32_f16 v[86:89], v[242:245], v[222:225], v[98:101]
	v_mfma_f32_16x16x32_f16 v[98:101], v[246:249], v[226:229], v[86:89]
	s_mov_b32 m0, s31
	s_barrier
	s_nop 2
	ds_read_b128 v[86:89], v213 offset:49152
	ds_read_b128 v[90:93], v213 offset:50176
	ds_read_b128 v[162:165], v213 offset:51200
	ds_read_b128 v[170:173], v213 offset:52224
	ds_read_b128 v[194:197], v213 offset:53248
	ds_read_b128 v[214:217], v213 offset:54272
	ds_read_b128 v[222:225], v213 offset:55296
	global_load_lds_dwordx4 v198, s[58:59]
	s_mov_b32 m0, s61
	ds_read_b128 v[226:229], v213 offset:56320
	global_load_lds_dwordx4 v202, s[58:59]
	s_barrier
	s_waitcnt lgkmcnt(0)
	s_waitcnt lgkmcnt(0)
	v_mfma_f32_16x16x32_f16 v[94:97], v[64:67], v[86:89], v[94:97]
	v_mfma_f32_16x16x32_f16 v[68:71], v[78:81], v[86:89], v[68:71]
	v_mfma_f32_16x16x32_f16 v[46:49], v[64:67], v[162:165], v[46:49]
	v_mfma_f32_16x16x32_f16 v[38:41], v[78:81], v[162:165], v[38:41]
	v_mfma_f32_16x16x32_f16 v[30:33], v[64:67], v[194:197], v[30:33]
	v_mfma_f32_16x16x32_f16 v[22:25], v[78:81], v[194:197], v[22:25]
	v_mfma_f32_16x16x32_f16 v[14:17], v[64:67], v[222:225], v[14:17]
	v_mfma_f32_16x16x32_f16 v[6:9], v[78:81], v[222:225], v[6:9]
	v_mfma_f32_16x16x32_f16 v[94:97], v[74:77], v[90:93], v[94:97]
	v_mfma_f32_16x16x32_f16 v[70:73], v[82:85], v[90:93], v[68:71]
	v_mfma_f32_16x16x32_f16 v[46:49], v[74:77], v[170:173], v[46:49]
	v_mfma_f32_16x16x32_f16 v[38:41], v[82:85], v[170:173], v[38:41]
	v_mfma_f32_16x16x32_f16 v[30:33], v[74:77], v[214:217], v[30:33]
	v_mfma_f32_16x16x32_f16 v[22:25], v[82:85], v[214:217], v[22:25]
	v_mfma_f32_16x16x32_f16 v[14:17], v[74:77], v[226:229], v[14:17]
	v_mfma_f32_16x16x32_f16 v[6:9], v[82:85], v[226:229], v[6:9]
	s_barrier
	s_add_u32 s22, s52, 0x80080
	s_addc_u32 s23, s53, 0
	s_add_i32 s52, s83, s5
	s_mov_b32 m0, s52
	s_nop 0
	global_load_lds_dwordx4 v178, s[22:23]
	s_add_i32 m0, s52, 0x2000
	s_nop 0
	global_load_lds_dwordx4 v174, s[22:23]
	s_waitcnt vmcnt(6)
	s_barrier
	v_mfma_f32_16x16x32_f16 v[60:63], v[234:237], v[86:89], v[60:63]
	v_mfma_f32_16x16x32_f16 v[50:53], v[242:245], v[86:89], v[50:53]
	v_mfma_f32_16x16x32_f16 v[42:45], v[234:237], v[162:165], v[42:45]
	v_mfma_f32_16x16x32_f16 v[34:37], v[242:245], v[162:165], v[34:37]
	v_mfma_f32_16x16x32_f16 v[26:29], v[234:237], v[194:197], v[26:29]
	v_mfma_f32_16x16x32_f16 v[18:21], v[242:245], v[194:197], v[18:21]
	v_mfma_f32_16x16x32_f16 v[10:13], v[234:237], v[222:225], v[10:13]
	v_mfma_f32_16x16x32_f16 v[2:5], v[242:245], v[222:225], v[2:5]
	v_mfma_f32_16x16x32_f16 v[74:77], v[238:241], v[90:93], v[60:63]
	v_mfma_f32_16x16x32_f16 v[50:53], v[246:249], v[90:93], v[50:53]
	v_mfma_f32_16x16x32_f16 v[42:45], v[238:241], v[170:173], v[42:45]
	v_mfma_f32_16x16x32_f16 v[34:37], v[246:249], v[170:173], v[34:37]
	v_mfma_f32_16x16x32_f16 v[26:29], v[238:241], v[214:217], v[26:29]
	v_mfma_f32_16x16x32_f16 v[18:21], v[246:249], v[214:217], v[18:21]
	v_mfma_f32_16x16x32_f16 v[10:13], v[238:241], v[226:229], v[10:13]
	v_mfma_f32_16x16x32_f16 v[2:5], v[246:249], v[226:229], v[2:5]
	s_add_i32 s81, s81, 2
	s_add_u32 s24, s24, 0x100
	s_addc_u32 s25, s25, 0
	s_add_u32 s50, s50, 0x100
	s_addc_u32 s51, s51, 0
	s_cmp_gt_u32 s81, 29
	s_barrier
	s_cbranch_scc1 .LBB0_616

;     __device__ __forceinline__ void prefetch(const Unit& u, int wr, int wc, int lane) const { lnfold_prefetch(vl, stats, gW, bW, u, wr, wc, lane); }
;     __device__ __forceinline__ void prefetch(const Unit& u, int wr, int wc, int lane) const { lnfold_prefetch(vl, stats, gW, bW, u, wr, wc, lane); }
; #define PG8_STAGE(bufoff, gbase, voff) do { _Pragma("unroll") for (int _i = 0; _i < 2; ++_i) \
;         __builtin_amdgcn_global_load_lds((const unsigned*)((const char*)(gbase) + (voff)[_i]), (LAS unsigned*)(lds + (bufoff) + ldsw + _i * 8192), 16, 0, 0); } while (0)
; #define PG8_LDA(dst, b, h) do { _Pragma("unroll") for (int m = 0; m < 4; ++m) _Pragma("unroll") for (int k = 0; k < 2; ++k) dst[m][k] = *(const LAS f16x8*)(lds + PG8_SA(b, h) + aoff + m * 2048 + k * 1024); } while (0)
; #define PG8_LDB(dst, b, h) do { _Pragma("unroll") for (int n = 0; n < 2; ++n) _Pragma("unroll") for (int k = 0; k < 2; ++k) dst[n][k] = *(const LAS f16x8*)(lds + PG8_SB(b, h) + boff + n * 2048 + k * 1024); } while (0)
; #define PG8_WAIT_V(n) asm volatile("s_waitcnt vmcnt(" #n ")" ::: "memory")
; #define PG8_WAIT_L(n) asm volatile("s_waitcnt lgkmcnt(" #n ")" ::: "memory")
; template <class Epi>
; __device__ __forceinline__ void gemm_phase(LAS unsigned char* lds, const Gemm g0, const StaticOrder& S, const Epi& E) {
;     ...
;         for (int t = 0; t < nt; t += 2) {
;             const bool last = (t == nt - 2);
;             if (Epi::PREF && last) E.prefetch(cur, wr, wc, lane);
;             const char* a1 = cA + (size_t)(t + 1) * kstep;
;             const char* a2 = last ? nA : cA + (size_t)(t + 2) * kstep; const char* b2 = last ? nB : cB + (size_t)(t + 2) * kstep;
;             const char* a3 = a2 + kstep; const char* b3 = b2 + kstep;
;             PG8_LDB(B0, 0, 0); PG8_SCHED; PG8_LDA(At, 0, 0); PG8_STAGE(PG8_SA(1, 1), a1 + hstep, voffA);
;             PG8_WAIT_L(8); PG8_BAR; PG8_WAIT_L(0); PG8_MMA(0, 0, At, B0); PG8_BAR; PG8_SCHED;
;             PG8_LDB(B1, 0, 1); PG8_STAGE(PG8_SB(0, 0), b2, voffB);
;             PG8_BAR; PG8_WAIT_L(0); PG8_MMA(0, 1, At, B1); PG8_BAR;
;             PG8_LDA(At, 0, 1); PG8_STAGE(PG8_SA(0, 0), a2, voffA);
;             PG8_BAR; PG8_WAIT_L(0); PG8_MMA(1, 0, At, B0); PG8_BAR; PG8_SCHED;
;             PG8_STAGE(PG8_SB(0, 1), b2 + hstep, voffB);
;             PG8_WAIT_V(6); PG8_BAR; PG8_MMA(1, 1, At, B1); PG8_BAR;
.LBB0_672:
	s_add_u32 s10, s12, 0x100
	s_addc_u32 s11, s13, 0
	s_add_i32 s23, 0, 0x10000
	ds_read_b128 v[130:133], v201
	ds_read_b128 v[134:137], v201 offset:1024
	ds_read_b128 v[138:141], v201 offset:2048
	ds_read_b128 v[142:145], v201 offset:3072
	s_cmpk_eq_i32 s22, 0x54
	s_cselect_b32 s81, s1, s11
	s_cselect_b32 s80, s0, s10
	s_cselect_b32 s63, s59, s25
	s_cselect_b32 s62, s58, s24
	s_add_i32 m0, s28, 0xc000
	ds_read_b128 v[146:149], v208
	ds_read_b128 v[150:153], v208 offset:1024
	ds_read_b128 v[154:157], v208 offset:2048
	ds_read_b128 v[162:165], v208 offset:3072
	ds_read_b128 v[170:173], v208 offset:4096
	ds_read_b128 v[184:187], v208 offset:5120
	ds_read_b128 v[188:191], v208 offset:6144
	global_load_lds_dwordx4 v182, s[12:13]
	s_add_i32 m0, s28, 0xe000
	ds_read_b128 v[192:195], v208 offset:7168
	global_load_lds_dwordx4 v180, s[12:13]
	s_waitcnt lgkmcnt(8)
	s_barrier
	s_waitcnt lgkmcnt(0)
	s_waitcnt lgkmcnt(0)
	v_mfma_f32_16x16x32_f16 v[126:129], v[130:133], v[146:149], v[126:129]
	v_mfma_f32_16x16x32_f16 v[122:125], v[138:141], v[146:149], v[122:125]
	v_mfma_f32_16x16x32_f16 v[110:113], v[130:133], v[154:157], v[110:113]
	v_mfma_f32_16x16x32_f16 v[106:109], v[138:141], v[154:157], v[106:109]
	v_mfma_f32_16x16x32_f16 v[94:97], v[130:133], v[170:173], v[94:97]
	v_mfma_f32_16x16x32_f16 v[90:93], v[138:141], v[170:173], v[90:93]
	v_mfma_f32_16x16x32_f16 v[78:81], v[130:133], v[188:191], v[78:81]
	v_mfma_f32_16x16x32_f16 v[74:77], v[138:141], v[188:191], v[74:77]
	v_mfma_f32_16x16x32_f16 v[126:129], v[134:137], v[150:153], v[126:129]
	v_mfma_f32_16x16x32_f16 v[122:125], v[142:145], v[150:153], v[122:125]
	v_mfma_f32_16x16x32_f16 v[110:113], v[134:137], v[162:165], v[110:113]
	v_mfma_f32_16x16x32_f16 v[106:109], v[142:145], v[162:165], v[106:109]
	v_mfma_f32_16x16x32_f16 v[94:97], v[134:137], v[184:187], v[94:97]
	v_mfma_f32_16x16x32_f16 v[90:93], v[142:145], v[184:187], v[90:93]
	v_mfma_f32_16x16x32_f16 v[78:81], v[134:137], v[192:195], v[78:81]
	v_mfma_f32_16x16x32_f16 v[74:77], v[142:145], v[192:195], v[74:77]
	s_barrier
	s_add_i32 s90, 0, 0x14000
	s_add_i32 s12, s23, s19
	ds_read_b128 v[196:199], v201 offset:16384
	ds_read_b128 v[210:213], v201 offset:17408
	s_mov_b32 m0, s12
	ds_read_b128 v[214:217], v201 offset:18432
	global_load_lds_dwordx4 v174, s[62:63]
	s_add_i32 m0, s12, 0x2000
	ds_read_b128 v[222:225], v201 offset:19456
	global_load_lds_dwordx4 v158, s[62:63]
	s_barrier
	s_waitcnt lgkmcnt(0)
	s_waitcnt lgkmcnt(0)
	v_mfma_f32_16x16x32_f16 v[118:121], v[196:199], v[146:149], v[118:121]
	v_mfma_f32_16x16x32_f16 v[114:117], v[214:217], v[146:149], v[114:117]
	v_mfma_f32_16x16x32_f16 v[102:105], v[196:199], v[154:157], v[102:105]
	v_mfma_f32_16x16x32_f16 v[98:101], v[214:217], v[154:157], v[98:101]
	v_mfma_f32_16x16x32_f16 v[86:89], v[196:199], v[170:173], v[86:89]
	v_mfma_f32_16x16x32_f16 v[82:85], v[214:217], v[170:173], v[82:85]
	v_mfma_f32_16x16x32_f16 v[70:73], v[196:199], v[188:191], v[70:73]
	v_mfma_f32_16x16x32_f16 v[66:69], v[214:217], v[188:191], v[66:69]
	v_mfma_f32_16x16x32_f16 v[118:121], v[210:213], v[150:153], v[118:121]
	v_mfma_f32_16x16x32_f16 v[114:117], v[222:225], v[150:153], v[114:117]
	v_mfma_f32_16x16x32_f16 v[102:105], v[210:213], v[162:165], v[102:105]
	v_mfma_f32_16x16x32_f16 v[98:101], v[222:225], v[162:165], v[98:101]
	v_mfma_f32_16x16x32_f16 v[86:89], v[210:213], v[184:187], v[86:89]
	v_mfma_f32_16x16x32_f16 v[82:85], v[222:225], v[184:187], v[82:85]
	v_mfma_f32_16x16x32_f16 v[70:73], v[210:213], v[192:195], v[70:73]
	v_mfma_f32_16x16x32_f16 v[66:69], v[222:225], v[192:195], v[66:69]
	s_mov_b32 m0, s28
	s_barrier
	ds_read_b128 v[146:149], v208 offset:16384
	ds_read_b128 v[150:153], v208 offset:17408
	ds_read_b128 v[154:157], v208 offset:18432
	ds_read_b128 v[162:165], v208 offset:19456
	ds_read_b128 v[170:173], v208 offset:20480
	ds_read_b128 v[184:187], v208 offset:21504
	ds_read_b128 v[188:191], v208 offset:22528
	global_load_lds_dwordx4 v176, s[80:81]
	s_mov_b32 m0, s29
	ds_read_b128 v[192:195], v208 offset:23552
	global_load_lds_dwordx4 v160, s[80:81]
	s_barrier
	s_waitcnt lgkmcnt(0)
	s_waitcnt lgkmcnt(0)
	v_mfma_f32_16x16x32_f16 v[62:65], v[130:133], v[146:149], v[62:65]
	v_mfma_f32_16x16x32_f16 v[58:61], v[138:141], v[146:149], v[58:61]
	v_mfma_f32_16x16x32_f16 v[46:49], v[130:133], v[154:157], v[46:49]
	v_mfma_f32_16x16x32_f16 v[42:45], v[138:141], v[154:157], v[42:45]
	v_mfma_f32_16x16x32_f16 v[30:33], v[130:133], v[170:173], v[30:33]
	v_mfma_f32_16x16x32_f16 v[26:29], v[138:141], v[170:173], v[26:29]
	v_mfma_f32_16x16x32_f16 v[14:17], v[130:133], v[188:191], v[14:17]
	v_mfma_f32_16x16x32_f16 v[10:13], v[138:141], v[188:191], v[10:13]
	v_mfma_f32_16x16x32_f16 v[62:65], v[134:137], v[150:153], v[62:65]
	v_mfma_f32_16x16x32_f16 v[58:61], v[142:145], v[150:153], v[58:61]
	v_mfma_f32_16x16x32_f16 v[46:49], v[134:137], v[162:165], v[46:49]
	v_mfma_f32_16x16x32_f16 v[42:45], v[142:145], v[162:165], v[42:45]
	v_mfma_f32_16x16x32_f16 v[30:33], v[134:137], v[184:187], v[30:33]
	v_mfma_f32_16x16x32_f16 v[26:29], v[142:145], v[184:187], v[26:29]
	v_mfma_f32_16x16x32_f16 v[14:17], v[134:137], v[192:195], v[14:17]
	v_mfma_f32_16x16x32_f16 v[10:13], v[142:145], v[192:195], v[10:13]
	s_barrier
	s_add_u32 s12, s62, 0x160000
	s_addc_u32 s13, s63, 0
	s_add_i32 s23, s90, s19
	s_mov_b32 m0, s23
	s_nop 0
	global_load_lds_dwordx4 v174, s[12:13]
	s_add_i32 m0, s23, 0x2000
	s_nop 0
	global_load_lds_dwordx4 v158, s[12:13]
	s_waitcnt vmcnt(6)
	s_barrier
; #define PG8_STAGE(bufoff, gbase, voff) do { _Pragma("unroll") for (int _i = 0; _i < 2; ++_i) \
;         __builtin_amdgcn_global_load_lds((const unsigned*)((const char*)(gbase) + (voff)[_i]), (LAS unsigned*)(lds + (bufoff) + ldsw + _i * 8192), 16, 0, 0); } while (0)
; #define PG8_LDA(dst, b, h) do { _Pragma("unroll") for (int m = 0; m < 4; ++m) _Pragma("unroll") for (int k = 0; k < 2; ++k) dst[m][k] = *(const LAS f16x8*)(lds + PG8_SA(b, h) + aoff + m * 2048 + k * 1024); } while (0)
; #define PG8_LDB(dst, b, h) do { _Pragma("unroll") for (int n = 0; n < 2; ++n) _Pragma("unroll") for (int k = 0; k < 2; ++k) dst[n][k] = *(const LAS f16x8*)(lds + PG8_SB(b, h) + boff + n * 2048 + k * 1024); } while (0)
; #define PG8_MMA(ai, bj, At, Bt) do { __builtin_amdgcn_s_setprio(1); _Pragma("unroll") for (int m = 0; m < 4; ++m) _Pragma("unroll") for (int n = 0; n < 2; ++n) _Pragma("unroll") for (int k = 0; k < 2; ++k) \
;         acc[ai][bj][m][n] = __builtin_amdgcn_mfma_f32_16x16x32_f16(Bt[n][k], At[m][k], acc[ai][bj][m][n], 0, 0, 0); __builtin_amdgcn_s_setprio(0); } while (0)
; #define PG8_WAIT_V(n) asm volatile("s_waitcnt vmcnt(" #n ")" ::: "memory")
; #define PG8_WAIT_L(n) asm volatile("s_waitcnt lgkmcnt(" #n ")" ::: "memory")
; #define PG8_BAR __builtin_amdgcn_s_barrier()
; #define PG8_SCHED __builtin_amdgcn_sched_barrier(0)
; template <class Epi>
; __device__ __forceinline__ void gemm_phase(LAS unsigned char* lds, const Gemm g0, const StaticOrder& S, const Epi& E) {
;     ...
;             PG8_WAIT_V(6); PG8_BAR; PG8_MMA(1, 1, At, B1); PG8_BAR;
;             PG8_LDB(B0, 1, 0); PG8_SCHED; PG8_LDA(At, 1, 0); PG8_STAGE(PG8_SA(0, 1), a2 + hstep, voffA);
;             PG8_WAIT_L(8); PG8_BAR; PG8_WAIT_L(0); PG8_MMA(0, 0, At, B0); PG8_BAR; PG8_SCHED;
;             PG8_LDB(B1, 1, 1); PG8_STAGE(PG8_SB(1, 0), b3, voffB);
;             PG8_BAR; PG8_WAIT_L(0); PG8_MMA(0, 1, At, B1); PG8_BAR;
;             PG8_LDA(At, 1, 1); PG8_STAGE(PG8_SA(1, 0), a3, voffA);
	v_mfma_f32_16x16x32_f16 v[54:57], v[196:199], v[146:149], v[54:57]
	v_mfma_f32_16x16x32_f16 v[50:53], v[214:217], v[146:149], v[50:53]
	v_mfma_f32_16x16x32_f16 v[38:41], v[196:199], v[154:157], v[38:41]
	v_mfma_f32_16x16x32_f16 v[34:37], v[214:217], v[154:157], v[34:37]
	v_mfma_f32_16x16x32_f16 v[22:25], v[196:199], v[170:173], v[22:25]
	v_mfma_f32_16x16x32_f16 v[18:21], v[214:217], v[170:173], v[18:21]
	v_mfma_f32_16x16x32_f16 v[6:9], v[196:199], v[188:191], v[6:9]
	v_mfma_f32_16x16x32_f16 v[2:5], v[214:217], v[188:191], v[2:5]
	v_mfma_f32_16x16x32_f16 v[54:57], v[210:213], v[150:153], v[54:57]
	v_mfma_f32_16x16x32_f16 v[50:53], v[222:225], v[150:153], v[50:53]
	v_mfma_f32_16x16x32_f16 v[38:41], v[210:213], v[162:165], v[38:41]
	v_mfma_f32_16x16x32_f16 v[34:37], v[222:225], v[162:165], v[34:37]
	v_mfma_f32_16x16x32_f16 v[22:25], v[210:213], v[184:187], v[22:25]
	v_mfma_f32_16x16x32_f16 v[18:21], v[222:225], v[184:187], v[18:21]
	v_mfma_f32_16x16x32_f16 v[6:9], v[210:213], v[192:195], v[6:9]
	v_mfma_f32_16x16x32_f16 v[2:5], v[222:225], v[192:195], v[2:5]
	s_add_i32 s23, 0, 0x18000
	s_barrier
	ds_read_b128 v[130:133], v201 offset:32768
	ds_read_b128 v[134:137], v201 offset:33792
	ds_read_b128 v[138:141], v201 offset:34816
	ds_read_b128 v[142:145], v201 offset:35840
	s_add_u32 s12, s80, 0x160000
	s_addc_u32 s13, s81, 0
	s_mov_b32 m0, s31
	ds_read_b128 v[146:149], v208 offset:32768
	ds_read_b128 v[150:153], v208 offset:33792
	ds_read_b128 v[154:157], v208 offset:34816
	ds_read_b128 v[162:165], v208 offset:35840
	ds_read_b128 v[170:173], v208 offset:36864
	ds_read_b128 v[184:187], v208 offset:37888
	ds_read_b128 v[188:191], v208 offset:38912
	global_load_lds_dwordx4 v176, s[12:13]
	s_mov_b32 m0, s61
	ds_read_b128 v[192:195], v208 offset:39936
	global_load_lds_dwordx4 v160, s[12:13]
	s_waitcnt lgkmcnt(8)
	s_barrier
	s_waitcnt lgkmcnt(0)
	s_waitcnt lgkmcnt(0)
	v_mfma_f32_16x16x32_f16 v[126:129], v[130:133], v[146:149], v[126:129]
	v_mfma_f32_16x16x32_f16 v[122:125], v[138:141], v[146:149], v[122:125]
	v_mfma_f32_16x16x32_f16 v[110:113], v[130:133], v[154:157], v[110:113]
	v_mfma_f32_16x16x32_f16 v[106:109], v[138:141], v[154:157], v[106:109]
	v_mfma_f32_16x16x32_f16 v[94:97], v[130:133], v[170:173], v[94:97]
	v_mfma_f32_16x16x32_f16 v[90:93], v[138:141], v[170:173], v[90:93]
	v_mfma_f32_16x16x32_f16 v[78:81], v[130:133], v[188:191], v[78:81]
	v_mfma_f32_16x16x32_f16 v[74:77], v[138:141], v[188:191], v[74:77]
	v_mfma_f32_16x16x32_f16 v[126:129], v[134:137], v[150:153], v[126:129]
	v_mfma_f32_16x16x32_f16 v[122:125], v[142:145], v[150:153], v[122:125]
	v_mfma_f32_16x16x32_f16 v[110:113], v[134:137], v[162:165], v[110:113]
	v_mfma_f32_16x16x32_f16 v[106:109], v[142:145], v[162:165], v[106:109]
	v_mfma_f32_16x16x32_f16 v[94:97], v[134:137], v[184:187], v[94:97]
	v_mfma_f32_16x16x32_f16 v[90:93], v[142:145], v[184:187], v[90:93]
	v_mfma_f32_16x16x32_f16 v[78:81], v[134:137], v[192:195], v[78:81]
	v_mfma_f32_16x16x32_f16 v[74:77], v[142:145], v[192:195], v[74:77]
	s_barrier
	s_add_i32 s90, 0, 0x1c000
	s_add_i32 s12, s23, s19
	s_mov_b32 m0, s12
	ds_read_b128 v[196:199], v201 offset:49152
	ds_read_b128 v[210:213], v201 offset:50176
	ds_read_b128 v[214:217], v201 offset:51200
	global_load_lds_dwordx4 v200, s[62:63]
	s_add_i32 m0, s12, 0x2000
	ds_read_b128 v[222:225], v201 offset:52224
	global_load_lds_dwordx4 v218, s[62:63]
	s_barrier
	s_waitcnt lgkmcnt(0)
	s_waitcnt lgkmcnt(0)
	v_mfma_f32_16x16x32_f16 v[118:121], v[196:199], v[146:149], v[118:121]
	v_mfma_f32_16x16x32_f16 v[114:117], v[214:217], v[146:149], v[114:117]
	v_mfma_f32_16x16x32_f16 v[102:105], v[196:199], v[154:157], v[102:105]
	v_mfma_f32_16x16x32_f16 v[98:101], v[214:217], v[154:157], v[98:101]
	v_mfma_f32_16x16x32_f16 v[86:89], v[196:199], v[170:173], v[86:89]
	v_mfma_f32_16x16x32_f16 v[82:85], v[214:217], v[170:173], v[82:85]
	v_mfma_f32_16x16x32_f16 v[70:73], v[196:199], v[188:191], v[70:73]
	v_mfma_f32_16x16x32_f16 v[66:69], v[214:217], v[188:191], v[66:69]
	v_mfma_f32_16x16x32_f16 v[118:121], v[210:213], v[150:153], v[118:121]
	v_mfma_f32_16x16x32_f16 v[114:117], v[222:225], v[150:153], v[114:117]
	v_mfma_f32_16x16x32_f16 v[102:105], v[210:213], v[162:165], v[102:105]
	v_mfma_f32_16x16x32_f16 v[98:101], v[222:225], v[162:165], v[98:101]
	v_mfma_f32_16x16x32_f16 v[86:89], v[210:213], v[184:187], v[86:89]
	v_mfma_f32_16x16x32_f16 v[82:85], v[222:225], v[184:187], v[82:85]
	v_mfma_f32_16x16x32_f16 v[70:73], v[210:213], v[192:195], v[70:73]
	v_mfma_f32_16x16x32_f16 v[66:69], v[222:225], v[192:195], v[66:69]
	s_mov_b32 m0, s83
	s_barrier
; #define GAS __attribute__((address_space(1)))
; #define PG8_STAGE(bufoff, gbase, voff) do { _Pragma("unroll") for (int _i = 0; _i < 2; ++_i) \
;         __builtin_amdgcn_global_load_lds((const unsigned*)((const char*)(gbase) + (voff)[_i]), (LAS unsigned*)(lds + (bufoff) + ldsw + _i * 8192), 16, 0, 0); } while (0)
; #define PG8_LDA(dst, b, h) do { _Pragma("unroll") for (int m = 0; m < 4; ++m) _Pragma("unroll") for (int k = 0; k < 2; ++k) dst[m][k] = *(const LAS f16x8*)(lds + PG8_SA(b, h) + aoff + m * 2048 + k * 1024); } while (0)
; #define PG8_MMA(ai, bj, At, Bt) do { __builtin_amdgcn_s_setprio(1); _Pragma("unroll") for (int m = 0; m < 4; ++m) _Pragma("unroll") for (int n = 0; n < 2; ++n) _Pragma("unroll") for (int k = 0; k < 2; ++k) \
;         acc[ai][bj][m][n] = __builtin_amdgcn_mfma_f32_16x16x32_f16(Bt[n][k], At[m][k], acc[ai][bj][m][n], 0, 0, 0); __builtin_amdgcn_s_setprio(0); } while (0)
; #define PG8_WAIT_V(n) asm volatile("s_waitcnt vmcnt(" #n ")" ::: "memory")
; #define PG8_WAIT_L(n) asm volatile("s_waitcnt lgkmcnt(" #n ")" ::: "memory")
; #define PG8_BAR __builtin_amdgcn_s_barrier()
; #define PG8_SCHED __builtin_amdgcn_sched_barrier(0)
;     __device__ __forceinline__ void operator()(f32x4 (&acc)[2][2][4][2], const Unit& u, int wr, int wc, int fr, int fq) const {
;     ...
;         { const int lane = fr + 16 * fq, cL = u.pn * BM + wc * 32 + (lane < 32 ? lane : 96 + lane);
;           float vg = 0.f, vb = 0.f, vt = 0.f;
;           if (hasln) { vg = *(const GAS float*)(pg + cL); vb = *(const GAS float*)(pb + cL); }
;           if (haszh) vt = *(const GAS float*)(tg + cL);
; template <class Epi>
; __device__ __forceinline__ void gemm_phase(LAS unsigned char* lds, const Gemm g0, const StaticOrder& S, const Epi& E) {
;     ...
;             PG8_LDA(At, 1, 1); PG8_STAGE(PG8_SA(1, 0), a3, voffA);
;             PG8_BAR; PG8_WAIT_L(0); PG8_MMA(1, 0, At, B0); PG8_BAR; PG8_SCHED;
;             PG8_STAGE(PG8_SB(1, 1), b3 + hstep, voffB);
;             PG8_WAIT_V(6); PG8_BAR; PG8_MMA(1, 1, At, B1); PG8_BAR;
;         }
	ds_read_b128 v[146:149], v208 offset:49152
	ds_read_b128 v[150:153], v208 offset:50176
	ds_read_b128 v[154:157], v208 offset:51200
	ds_read_b128 v[162:165], v208 offset:52224
	ds_read_b128 v[170:173], v208 offset:53248
	ds_read_b128 v[184:187], v208 offset:54272
	ds_read_b128 v[188:191], v208 offset:55296
	global_load_lds_dwordx4 v226, s[80:81]
	s_mov_b32 m0, s84
	ds_read_b128 v[192:195], v208 offset:56320
	global_load_lds_dwordx4 v228, s[80:81]
	s_barrier
	s_waitcnt lgkmcnt(0)
	s_waitcnt lgkmcnt(0)
	v_mfma_f32_16x16x32_f16 v[62:65], v[130:133], v[146:149], v[62:65]
	v_mfma_f32_16x16x32_f16 v[58:61], v[138:141], v[146:149], v[58:61]
	v_mfma_f32_16x16x32_f16 v[46:49], v[130:133], v[154:157], v[46:49]
	v_mfma_f32_16x16x32_f16 v[42:45], v[138:141], v[154:157], v[42:45]
	v_mfma_f32_16x16x32_f16 v[30:33], v[130:133], v[170:173], v[30:33]
	v_mfma_f32_16x16x32_f16 v[26:29], v[138:141], v[170:173], v[26:29]
	v_mfma_f32_16x16x32_f16 v[14:17], v[130:133], v[188:191], v[14:17]
	v_mfma_f32_16x16x32_f16 v[10:13], v[138:141], v[188:191], v[10:13]
	v_mfma_f32_16x16x32_f16 v[62:65], v[134:137], v[150:153], v[62:65]
	v_mfma_f32_16x16x32_f16 v[58:61], v[142:145], v[150:153], v[58:61]
	v_mfma_f32_16x16x32_f16 v[46:49], v[134:137], v[162:165], v[46:49]
	v_mfma_f32_16x16x32_f16 v[42:45], v[142:145], v[162:165], v[42:45]
	v_mfma_f32_16x16x32_f16 v[30:33], v[134:137], v[184:187], v[30:33]
	v_mfma_f32_16x16x32_f16 v[26:29], v[142:145], v[184:187], v[26:29]
	v_mfma_f32_16x16x32_f16 v[14:17], v[134:137], v[192:195], v[14:17]
	v_mfma_f32_16x16x32_f16 v[10:13], v[142:145], v[192:195], v[10:13]
	s_barrier
	s_add_u32 s12, s62, 0x160080
	s_addc_u32 s13, s63, 0
	s_add_i32 s23, s90, s19
	s_mov_b32 m0, s23
	s_nop 0
	global_load_lds_dwordx4 v174, s[12:13]
	s_add_i32 m0, s23, 0x2000
	s_nop 0
	global_load_lds_dwordx4 v158, s[12:13]
	s_waitcnt vmcnt(6)
	s_barrier
	v_mfma_f32_16x16x32_f16 v[54:57], v[196:199], v[146:149], v[54:57]
	v_mfma_f32_16x16x32_f16 v[50:53], v[214:217], v[146:149], v[50:53]
	v_mfma_f32_16x16x32_f16 v[38:41], v[196:199], v[154:157], v[38:41]
	v_mfma_f32_16x16x32_f16 v[34:37], v[214:217], v[154:157], v[34:37]
	v_mfma_f32_16x16x32_f16 v[22:25], v[196:199], v[170:173], v[22:25]
	v_mfma_f32_16x16x32_f16 v[18:21], v[214:217], v[170:173], v[18:21]
	v_mfma_f32_16x16x32_f16 v[6:9], v[196:199], v[188:191], v[6:9]
	v_mfma_f32_16x16x32_f16 v[2:5], v[214:217], v[188:191], v[2:5]
	v_mfma_f32_16x16x32_f16 v[54:57], v[210:213], v[150:153], v[54:57]
	v_mfma_f32_16x16x32_f16 v[50:53], v[222:225], v[150:153], v[50:53]
	v_mfma_f32_16x16x32_f16 v[38:41], v[210:213], v[162:165], v[38:41]
	v_mfma_f32_16x16x32_f16 v[34:37], v[222:225], v[162:165], v[34:37]
	v_mfma_f32_16x16x32_f16 v[22:25], v[210:213], v[184:187], v[22:25]
	v_mfma_f32_16x16x32_f16 v[18:21], v[222:225], v[184:187], v[18:21]
	v_mfma_f32_16x16x32_f16 v[6:9], v[210:213], v[192:195], v[6:9]
	v_mfma_f32_16x16x32_f16 v[2:5], v[222:225], v[192:195], v[2:5]
	s_add_i32 s22, s22, 2
	s_add_u32 s24, s24, 0x100
	s_addc_u32 s25, s25, 0
	s_cmpk_gt_u32 s22, 0x55
	s_mov_b64 s[12:13], s[10:11]
	s_barrier
	s_cbranch_scc0 .LBB0_672
	s_lshl_b32 s10, s92, 8
	s_or_b32 s12, s10, s82
	v_add_u32_e32 v130, s12, v204
	v_ashrrev_i32_e32 v131, 31, v130
	v_lshlrev_b64 v[132:133], 2, v[130:131]
	v_lshl_add_u64 v[134:135], s[38:39], 0, v[132:133]
	v_lshl_add_u64 v[132:133], s[48:49], 0, v[132:133]
	global_load_dword v146, v[134:135], off
	global_load_dword v147, v[132:133], off
	v_readlane_b32 s22, v254, 55
	v_readlane_b32 s23, v254, 56
	s_andn2_b64 vcc, exec, s[22:23]
	v_mov_b32_e32 v148, 0
	v_cndmask_b32_e64 v132, 0, 1, s[22:23]
	v_cmp_ne_u32_e64 s[10:11], 1, v132
	s_cbranch_vccnz .LBB0_675
	v_lshl_add_u64 v[130:131], v[130:131], 2, s[50:51]
	global_load_dword v148, v[130:131], off
